# SWA sink logits loaded with Q in the item prologue instead of fetched and waited for in the item epilogue
# speedup vs baseline: 1.0101x; 1.0012x over previous
; __device__ __forceinline__ unsigned pkbf(float lo, float hi) { f32x2_t v = {lo, hi}; bf16x2_t b = __builtin_convertvector(v, bf16x2_t); return __builtin_bit_cast(unsigned, b); }
; __device__ __forceinline__ void store_group(const f32x4 (&Og)[4], float inv, bf16_t* orow, int g) {
; #pragma unroll
;     for (int db = 0; db < 4; ++db) { u32x2 w; w.x = pkbf(Og[db][0] * inv, Og[db][1] * inv); w.y = pkbf(Og[db][2] * inv, Og[db][3] * inv);
;         *(u32x2*)(orow + 16 * db + 4 * g) = w; }
; __device__ __forceinline__ void swa_phase(LAS unsigned char* lds, const bf16_t* Q, const bf16_t* K, const bf16_t* V, bf16_t* Ob, const float* sink, float negb) {
;     ...
;         for (int grp = 0; grp < 4; ++grp) { const float lt = red_sum4(ls[grp]) + __builtin_amdgcn_exp2f(sink[4 * kvh + grp] * LOG2E + negb);
;             store_group(O[grp], __builtin_amdgcn_rcpf(lt), Ob + qrow * DM + (4 * kvh + grp) * 64, g); }
.LBB0_342:
	v_mov_b32_e32 v4, v158
	v_mov_b32_e32 v100, v159
	v_mov_b32_e32 v102, v184
	v_mov_b32_e32 v103, v185
	v_mov_b32_e32 v5, v131
	s_mov_b32 s0, 0x3fb8aa3b
	s_nop 0
	v_permlane16_swap_b32_e32 v131, v5
	v_add_f32_e32 v5, v131, v5
	v_mov_b32_e32 v8, v5
	s_nop 1
	v_permlane32_swap_b32_e32 v5, v8
	v_add_f32_e32 v5, v5, v8
	s_lshl_b32 s82, s37, 1
	v_readlane_b32 s52, v240, 27
	v_readlane_b32 s50, v240, 29
	s_add_i32 s41, s41, 1
	v_readlane_b32 s53, v240, 28
	v_readlane_b32 s51, v240, 30
	s_waitcnt vmcnt(0) lgkmcnt(0)
	v_fma_f32 v4, v4, s0, -v186
	v_exp_f32_e32 v4, v4
	s_nop 0
	v_add_f32_e32 v4, v5, v4
	v_rcp_f32_e32 v8, v4
	v_lshl_add_u64 v[4:5], v[124:125], 0, v[126:127]
	v_lshl_add_u64 v[10:11], v[4:5], 0, s[82:83]
	s_or_b32 s82, s36, 0x80
	v_pk_mul_f32 v[12:13], v[64:65], v[8:9] op_sel_hi:[1,0]
	v_pk_mul_f32 v[14:15], v[66:67], v[8:9] op_sel_hi:[1,0]
	v_pk_mul_f32 v[16:17], v[60:61], v[8:9] op_sel_hi:[1,0]
	v_pk_mul_f32 v[18:19], v[62:63], v[8:9] op_sel_hi:[1,0]
	v_pk_mul_f32 v[20:21], v[56:57], v[8:9] op_sel_hi:[1,0]
	v_pk_mul_f32 v[22:23], v[58:59], v[8:9] op_sel_hi:[1,0]
	v_pk_mul_f32 v[24:25], v[52:53], v[8:9] op_sel_hi:[1,0]
	v_pk_mul_f32 v[8:9], v[54:55], v[8:9] op_sel_hi:[1,0]
	v_cvt_pk_bf16_f32 v12, v12, v13
	v_cvt_pk_bf16_f32 v13, v14, v15
	v_cvt_pk_bf16_f32 v14, v16, v17
	v_cvt_pk_bf16_f32 v15, v18, v19
	v_cvt_pk_bf16_f32 v16, v20, v21
	v_cvt_pk_bf16_f32 v17, v22, v23
	v_cvt_pk_bf16_f32 v18, v24, v25
	v_cvt_pk_bf16_f32 v19, v8, v9
	global_store_dwordx2 v[10:11], v[12:13], off
	global_store_dwordx2 v[10:11], v[14:15], off offset:32
	global_store_dwordx2 v[10:11], v[16:17], off offset:64
	global_store_dwordx2 v[10:11], v[18:19], off offset:96
	v_mov_b32_e32 v8, v100
	v_mov_b32_e32 v9, v130
	s_nop 1
	v_permlane16_swap_b32_e32 v130, v9
	v_add_f32_e32 v9, v130, v9
	v_mov_b32_e32 v10, v9
	s_nop 1
	v_permlane32_swap_b32_e32 v9, v10
	v_add_f32_e32 v9, v9, v10
	v_lshl_add_u64 v[10:11], v[4:5], 0, s[82:83]
	s_or_b32 s82, s36, 0x100
	v_fma_f32 v8, v8, s0, -v186
	v_exp_f32_e32 v8, v8
	s_nop 0
	v_add_f32_e32 v8, v9, v8
	v_rcp_f32_e32 v8, v8
	s_nop 0
	v_pk_mul_f32 v[12:13], v[48:49], v[8:9] op_sel_hi:[1,0]
	v_pk_mul_f32 v[14:15], v[50:51], v[8:9] op_sel_hi:[1,0]
	v_pk_mul_f32 v[16:17], v[44:45], v[8:9] op_sel_hi:[1,0]
	v_pk_mul_f32 v[18:19], v[46:47], v[8:9] op_sel_hi:[1,0]
	v_pk_mul_f32 v[20:21], v[40:41], v[8:9] op_sel_hi:[1,0]
	v_pk_mul_f32 v[22:23], v[42:43], v[8:9] op_sel_hi:[1,0]
	v_pk_mul_f32 v[24:25], v[36:37], v[8:9] op_sel_hi:[1,0]
	v_pk_mul_f32 v[8:9], v[38:39], v[8:9] op_sel_hi:[1,0]
	v_cvt_pk_bf16_f32 v12, v12, v13
	v_cvt_pk_bf16_f32 v13, v14, v15
	v_cvt_pk_bf16_f32 v14, v16, v17
	v_cvt_pk_bf16_f32 v15, v18, v19
	v_cvt_pk_bf16_f32 v16, v20, v21
	v_cvt_pk_bf16_f32 v17, v22, v23
	v_cvt_pk_bf16_f32 v18, v24, v25
	v_cvt_pk_bf16_f32 v19, v8, v9
	global_store_dwordx2 v[10:11], v[12:13], off
	global_store_dwordx2 v[10:11], v[14:15], off offset:32
	global_store_dwordx2 v[10:11], v[16:17], off offset:64
	global_store_dwordx2 v[10:11], v[18:19], off offset:96
	v_mov_b32_e32 v8, v102
	v_mov_b32_e32 v9, v129
	s_nop 1
	v_permlane16_swap_b32_e32 v129, v9
	v_add_f32_e32 v9, v129, v9
	v_mov_b32_e32 v10, v9
	s_nop 1
	v_permlane32_swap_b32_e32 v9, v10
	v_add_f32_e32 v9, v9, v10
	v_lshl_add_u64 v[10:11], v[4:5], 0, s[82:83]
	s_or_b32 s82, s36, 0x180
	v_lshl_add_u64 v[4:5], v[4:5], 0, s[82:83]
	v_fma_f32 v8, v8, s0, -v186
	v_exp_f32_e32 v8, v8
	s_nop 0
	v_add_f32_e32 v8, v9, v8
	v_rcp_f32_e32 v8, v8
	s_nop 0
	v_pk_mul_f32 v[12:13], v[72:73], v[8:9] op_sel_hi:[1,0]
	v_pk_mul_f32 v[14:15], v[74:75], v[8:9] op_sel_hi:[1,0]
	v_pk_mul_f32 v[16:17], v[84:85], v[8:9] op_sel_hi:[1,0]
	v_pk_mul_f32 v[18:19], v[86:87], v[8:9] op_sel_hi:[1,0]
	v_pk_mul_f32 v[20:21], v[88:89], v[8:9] op_sel_hi:[1,0]
	v_pk_mul_f32 v[22:23], v[90:91], v[8:9] op_sel_hi:[1,0]
	v_pk_mul_f32 v[24:25], v[96:97], v[8:9] op_sel_hi:[1,0]
	v_pk_mul_f32 v[8:9], v[98:99], v[8:9] op_sel_hi:[1,0]
	v_cvt_pk_bf16_f32 v12, v12, v13
	v_cvt_pk_bf16_f32 v13, v14, v15
	v_cvt_pk_bf16_f32 v14, v16, v17
	v_cvt_pk_bf16_f32 v15, v18, v19
	v_cvt_pk_bf16_f32 v16, v20, v21
	v_cvt_pk_bf16_f32 v17, v22, v23
	v_cvt_pk_bf16_f32 v18, v24, v25
	v_cvt_pk_bf16_f32 v19, v8, v9
	global_store_dwordx2 v[10:11], v[12:13], off
	global_store_dwordx2 v[10:11], v[14:15], off offset:32
	global_store_dwordx2 v[10:11], v[16:17], off offset:64
	global_store_dwordx2 v[10:11], v[18:19], off offset:96
	v_mov_b32_e32 v6, v103
	v_mov_b32_e32 v7, v128
	s_nop 1
	v_permlane16_swap_b32_e32 v128, v7
	v_add_f32_e32 v7, v128, v7
	v_mov_b32_e32 v8, v7
	s_nop 1
	v_permlane32_swap_b32_e32 v7, v8
	v_add_f32_e32 v7, v7, v8
	v_fma_f32 v6, v6, s0, -v186
	v_exp_f32_e32 v6, v6
	s_nop 0
	v_add_f32_e32 v6, v7, v6
	v_rcp_f32_e32 v6, v6
	s_nop 0
	v_pk_mul_f32 v[8:9], v[68:69], v[6:7] op_sel_hi:[1,0]
	v_pk_mul_f32 v[10:11], v[70:71], v[6:7] op_sel_hi:[1,0]
	v_pk_mul_f32 v[12:13], v[76:77], v[6:7] op_sel_hi:[1,0]
	v_pk_mul_f32 v[14:15], v[78:79], v[6:7] op_sel_hi:[1,0]
	v_pk_mul_f32 v[16:17], v[80:81], v[6:7] op_sel_hi:[1,0]
	v_pk_mul_f32 v[18:19], v[82:83], v[6:7] op_sel_hi:[1,0]
	v_pk_mul_f32 v[20:21], v[92:93], v[6:7] op_sel_hi:[1,0]
	v_pk_mul_f32 v[6:7], v[94:95], v[6:7] op_sel_hi:[1,0]
	v_cvt_pk_bf16_f32 v8, v8, v9
	v_cvt_pk_bf16_f32 v9, v10, v11
	v_cvt_pk_bf16_f32 v10, v12, v13
	v_cvt_pk_bf16_f32 v11, v14, v15
	v_cvt_pk_bf16_f32 v12, v16, v17
	v_cvt_pk_bf16_f32 v13, v18, v19
	v_cvt_pk_bf16_f32 v14, v20, v21
	v_cvt_pk_bf16_f32 v15, v6, v7
	global_store_dwordx2 v[4:5], v[8:9], off
	global_store_dwordx2 v[4:5], v[10:11], off offset:32
	global_store_dwordx2 v[4:5], v[12:13], off offset:64
	global_store_dwordx2 v[4:5], v[14:15], off offset:96

; #define LAS __attribute__((address_space(3)))
; __device__ __forceinline__ void drain_wait() { asm volatile("s_waitcnt vmcnt(0)" ::: "memory"); __syncthreads(); }
; __device__ __forceinline__ void swa_phase(LAS unsigned char* lds, const bf16_t* Q, const bf16_t* K, const bf16_t* V, bf16_t* Ob, const float* sink, float negb) {
;     ...
;         const int item = item_of(it, SW_ITEMS, SW_ITEMS); if (item < 0) break;
;         const int b = item >> 8, kvh = (item >> 6) & 3, tb = item & 63;
;         const size_t ctx0 = (size_t)(MLAT + b * NCTX), lat0 = (size_t)(b * SEQ);
;         const int i_lo = tb == 0 ? 2 : 0, i_hi = tb == 63 ? 4 : 6;
;         const int NT = 4 + (i_hi - i_lo);
;         const DmaLane dl = dma_lane(256, kvh * 64, w, lane);
;     ...
;         dma_tile<1>(lds, K, V, SW_ROW0(0), 256, dl, w);
;         dma_tile<1>(lds + SW_BUF, K, V, SW_ROW0(1), 256, dl, w);
;         dma_tile<1>(lds + 2 * SW_BUF, K, V, SW_ROW0(2), 256, dl, w);
;         const int tq = 128 * tb + 16 * w;
;         const size_t qrow = (size_t)(b * SEQ + tq + l15);
;         bf16x8 qf[4][2];
; #pragma unroll
;         for (int grp = 0; grp < 4; ++grp)
; #pragma unroll
;             for (int ds = 0; ds < 2; ++ds) qf[grp][ds] = *(const bf16x8*)(Q + qrow * DM + (4 * kvh + grp) * 64 + 32 * ds + 8 * g);
;         f32x4 O[4][4]; float ls[4];
; #pragma unroll
;         for (int grp = 0; grp < 4; ++grp) { ls[grp] = 0.f;
; #pragma unroll
;             for (int db = 0; db < 4; ++db) O[grp][db] = (f32x4){0.f, 0.f, 0.f, 0.f}; }
;         drain_wait();
;         for (int t = 0; t < 4; ++t) {
;             dma_tile<1>(lds + ((t + 3) & 3) * SW_BUF, K, V, SW_ROW0(t + 3), 256, dl, w);
;             const LAS unsigned char* buf = lds + (t & 3) * SW_BUF;
;             full_tile<0, 2, 2>(O, ls, qf, negb, buf, buf + 8192, lane, 0);
.LBB0_350:
	s_cmp_lt_i32 s6, 0
	s_cbranch_scc1 .LBB0_357
	s_and_b32 s0, s6, 0x7fffff00
	s_add_i32 s82, s0, 0x8000
	s_lshl_b32 s0, s6, 5
	s_bfe_u32 s42, s6, 0x20006
	s_and_b32 s12, s6, 63
	s_and_b32 s43, s0, 0x7fffe000
	s_cmp_eq_u32 s12, 0
	s_cselect_b32 s7, 2, 0
	s_cmp_eq_u32 s12, 63
	s_cselect_b32 s0, 4, 6
	s_sub_i32 s44, s0, s7
	s_lshl_b64 s[8:9], s[82:83], 9
	s_add_u32 s0, s67, s8
	s_addc_u32 s1, s4, s9
	v_lshl_or_b32 v4, s42, 7, v188
	s_add_u32 s10, s5, s8
	v_or_b32_e32 v212, v4, v189
	s_addc_u32 s11, s58, s9
	s_add_i32 s6, s40, 0x2000
	s_mov_b32 s13, m0
	s_mov_b32 m0, s40
	s_nop 0
	global_load_lds_dwordx4 v212, s[0:1]
	s_mov_b32 m0, s13
	v_or_b32_e32 v213, v4, v190
	s_mov_b32 s0, m0
	s_mov_b32 m0, s6
	s_nop 0
	global_load_lds_dwordx4 v213, s[10:11]
	s_mov_b32 m0, s0
	s_or_b32 s6, s8, 0x8000
	s_add_u32 s0, s67, s6
	s_addc_u32 s1, s4, s9
	s_add_u32 s10, s5, s6
	s_addc_u32 s11, s58, s9
	s_add_i32 s6, s40, 0x4000
	s_mov_b32 s14, m0
	s_mov_b32 m0, s6
	s_nop 0
	global_load_lds_dwordx4 v212, s[0:1]
	s_mov_b32 m0, s14
	s_add_i32 s13, s40, 0x6000
	s_mov_b32 s0, m0
	s_mov_b32 m0, s13
	s_nop 0
	global_load_lds_dwordx4 v213, s[10:11]
	s_mov_b32 m0, s0
	s_or_b32 s6, s8, 0x10000
	s_add_u32 s0, s67, s6
	s_addc_u32 s1, s4, s9
	s_add_u32 s10, s5, s6
	s_addc_u32 s11, s58, s9
	s_add_i32 s6, s40, 0x8000
	s_mov_b32 s14, m0
	s_mov_b32 m0, s6
	s_nop 0
	global_load_lds_dwordx4 v212, s[0:1]
	s_mov_b32 m0, s14
	s_add_i32 s13, s40, 0xa000
	s_mov_b32 s0, m0
	s_mov_b32 m0, s13
	s_nop 0
	global_load_lds_dwordx4 v213, s[10:11]
	s_mov_b32 m0, s0
	s_lshl_b32 s45, s12, 7
	s_add_i32 s0, s45, s39
	s_add_i32 s1, s0, s43
	v_or_b32_e32 v4, s1, v187
	v_ashrrev_i32_e32 v5, 31, v4
	v_lshlrev_b64 v[126:127], 11, v[4:5]
	v_lshl_add_u64 v[4:5], v[122:123], 0, v[126:127]
	s_lshl_b32 s36, s42, 9
	s_mov_b32 s37, s83
	v_lshl_add_u64 v[32:33], v[4:5], 0, s[36:37]
	global_load_dwordx4 v[4:7], v[32:33], off
	global_load_dwordx4 v[8:11], v[32:33], off offset:128
	global_load_dwordx4 v[12:15], v[32:33], off offset:64
	global_load_dwordx4 v[16:19], v[32:33], off offset:192
	global_load_dwordx4 v[20:23], v[32:33], off offset:256
	global_load_dwordx4 v[24:27], v[32:33], off offset:320
	global_load_dwordx4 v[28:31], v[32:33], off offset:384
	s_nop 0
	global_load_dwordx4 v[32:35], v[32:33], off offset:448
	s_lshl_b32 s60, s42, 4
	s_mov_b32 s61, 0
	v_lshl_add_u64 v[214:215], v[120:121], 0, s[60:61]
	global_load_dword v158, v[214:215], off
	global_load_dword v159, v[214:215], off offset:4
	global_load_dword v184, v[214:215], off offset:8
	global_load_dword v185, v[214:215], off offset:12
	s_lshl_b32 s37, s42, 8
	s_add_i32 s46, s44, 4
	s_or_b32 s1, s8, 0x18000
	s_add_u32 s10, s67, s1
	s_addc_u32 s11, s4, s9
	s_add_u32 s8, s5, s1
	s_addc_u32 s9, s58, s9
	s_add_i32 s1, s40, 0xc000
	s_waitcnt vmcnt(0)
	s_barrier
	s_mov_b32 s12, m0
	s_mov_b32 m0, s1
	s_nop 0
	global_load_lds_dwordx4 v212, s[10:11]
	s_mov_b32 m0, s12
	v_add_u32_e32 v91, v154, v192
	s_add_i32 s6, s40, 0xe000
	s_mov_b32 s1, m0
	s_mov_b32 m0, s6
	s_nop 0
	global_load_lds_dwordx4 v213, s[8:9]
	s_mov_b32 m0, s1
	v_mov_b32_e32 v64, 0
	v_mov_b32_e32 v65, 0
	v_mov_b32_e32 v66, 0
	v_mov_b32_e32 v67, 0
	v_mov_b32_e32 v60, 0
	v_mov_b32_e32 v61, 0
	v_mov_b32_e32 v62, 0
	v_mov_b32_e32 v63, 0
	v_mov_b32_e32 v56, 0
	v_mov_b32_e32 v57, 0
	v_mov_b32_e32 v58, 0
	v_mov_b32_e32 v59, 0
	v_mov_b32_e32 v52, 0
	v_mov_b32_e32 v53, 0
	v_mov_b32_e32 v54, 0
	v_mov_b32_e32 v55, 0
	v_mov_b32_e32 v131, 0
	v_mov_b32_e32 v48, 0
	v_mov_b32_e32 v49, 0
	v_mov_b32_e32 v50, 0
	v_mov_b32_e32 v51, 0
	v_mov_b32_e32 v44, 0
	v_mov_b32_e32 v45, 0
	v_mov_b32_e32 v46, 0
	v_mov_b32_e32 v47, 0
	v_mov_b32_e32 v40, 0
	v_mov_b32_e32 v41, 0
	v_mov_b32_e32 v42, 0
	v_mov_b32_e32 v43, 0
	v_mov_b32_e32 v36, 0
	v_mov_b32_e32 v37, 0
	v_mov_b32_e32 v38, 0
	v_mov_b32_e32 v39, 0
	v_mov_b32_e32 v130, 0
	v_mov_b32_e32 v72, 0
	v_mov_b32_e32 v73, 0
	v_mov_b32_e32 v74, 0
	v_mov_b32_e32 v75, 0
	v_mov_b32_e32 v84, 0
	v_mov_b32_e32 v85, 0
	v_mov_b32_e32 v86, 0
	v_mov_b32_e32 v87, 0
	v_mov_b32_e32 v88, 0
	v_mov_b32_e32 v89, 0
	v_mov_b32_e32 v90, 0
	v_mov_b32_e32 v91, 0
	v_mov_b32_e32 v96, 0
	v_mov_b32_e32 v97, 0
	v_mov_b32_e32 v98, 0
	v_mov_b32_e32 v99, 0
	v_mov_b32_e32 v129, 0
	v_mov_b32_e32 v68, 0
	v_mov_b32_e32 v69, 0
	v_mov_b32_e32 v70, 0
	v_mov_b32_e32 v71, 0
	v_mov_b32_e32 v76, 0
	v_mov_b32_e32 v77, 0
	v_mov_b32_e32 v78, 0
	v_mov_b32_e32 v79, 0
	v_mov_b32_e32 v80, 0
	v_mov_b32_e32 v81, 0
	v_mov_b32_e32 v82, 0
	v_mov_b32_e32 v83, 0
	v_mov_b32_e32 v92, 0
	v_mov_b32_e32 v93, 0
	v_mov_b32_e32 v94, 0
	v_mov_b32_e32 v95, 0
	v_mov_b32_e32 v128, 0
	s_lshl_b32 s47, s7, 6
	s_add_i32 s7, s45, s47
	s_addk_i32 s7, 0xff80
	s_ashr_i32 s8, s7, 31
	s_add_u32 s7, s43, s7
	s_addc_u32 s8, 0, s8
	s_mov_b32 s1, 0
	s_mov_b32 s6, 4
	s_mov_b32 s34, 0
	v_add_u32_e32 v100, s34, v191
	v_add3_u32 v135, s34, v203, v198
	v_add_u32_e32 v102, v100, v193
	v_add_u32_e32 v100, v100, v192
	ds_read_b128 v[160:163], v100
	ds_read_b128 v[164:167], v102
	ds_read_b128 v[168:171], v100 offset:2048
	ds_read_b128 v[172:175], v102 offset:2048
	ds_read_b128 v[104:107], v100 offset:4096
	ds_read_b128 v[108:111], v102 offset:4096
	ds_read_b128 v[112:115], v100 offset:6144
	ds_read_b128 v[116:119], v102 offset:6144
	v_add_u32_e32 v103, v135, v199
	v_add_u32_e32 v133, v135, v200
	v_add_u32_e32 v134, v135, v201
	v_add_u32_e32 v135, v135, v202
	s_waitcnt lgkmcnt(4)
; #define LAS __attribute__((address_space(3)))
; __device__ __forceinline__ s16x4 vtr(const LAS unsigned char* p) { return __builtin_bit_cast(s16x4, __builtin_amdgcn_ds_read_tr16_b64_v4i16((LAS v4i16_t*)p)); }
; __device__ __forceinline__ bf16x8 cat8(s16x4 a, s16x4 b) { return (bf16x8){a[0], a[1], a[2], a[3], b[0], b[1], b[2], b[3]}; }
; __device__ __forceinline__ bf16x8 pack8(const f32x4& a, const f32x4& b) { u32x4 w; w.x = pkbf(a[0], a[1]); w.y = pkbf(a[2], a[3]); w.z = pkbf(b[0], b[1]); w.w = pkbf(b[2], b[3]); return __builtin_bit_cast(bf16x8, w); }
;     ...
;     for (int gh = 0; gh < 4 / GPB; ++gh) {
;         f32x4 S[GPB][4];
; #pragma unroll
;         for (int kb = 0; kb < 4; ++kb) {
;             const bf16x8 kf0 = *(const LAS bf16x8*)(kb0 + (16 * kb) * 128 + kx0), kf1 = *(const LAS bf16x8*)(kb0 + (16 * kb) * 128 + kx1);
; #pragma unroll
;             for (int gi = 0; gi < GPB; ++gi) { S[gi][kb] = __builtin_amdgcn_mfma_f32_16x16x32_bf16(kf0, qf[GPB * gh + gi][0], cinit, 0, 0, 0);
;                 S[gi][kb] = __builtin_amdgcn_mfma_f32_16x16x32_bf16(kf1, qf[GPB * gh + gi][1], S[gi][kb], 0, 0, 0); } }
;         bf16x8 pf[GPB][2];
; #pragma unroll
;         for (int gi = 0; gi < GPB; ++gi) {
;             if (MASK) {
; #pragma unroll
;                 for (int kb = 0; kb < 4; ++kb)
; #pragma unroll
;                     for (int i = 0; i < 4; ++i) { const int rel = rel0 + 16 * kb + 4 * g + i; S[gi][kb][i] = ((unsigned)(rel + 128) > 256u) ? NEGBIG : S[gi][kb][i]; }
;             }
;             ls[GPB * gh + gi] += exp_step<4>(S[gi]);
;             pf[gi][0] = pack8(S[gi][0], S[gi][1]); pf[gi][1] = pack8(S[gi][2], S[gi][3]);
;         }
; #pragma unroll
;         for (int kc = 0; kc < 2; ++kc)
; #pragma unroll
;             for (int db = 0; db < 4; ++db) {
;                 const LAS unsigned char* va = vrow + ((db ^ swz) << 5) + (32 * kc) * 128;
;                 const bf16x8 vf = cat8(vtr(va), vtr(va + 16 * 128));
; #pragma unroll
;                 for (int gi = 0; gi < GPB; ++gi) O[GPB * gh + gi][db] = __builtin_amdgcn_mfma_f32_16x16x32_bf16(vf, pf[gi][kc], O[GPB * gh + gi][db], 0, 0, 0);
;             }
	v_mfma_f32_16x16x32_bf16 v[136:139], v[160:163], v[4:7], v[0:3]
	v_mfma_f32_16x16x32_bf16 v[140:143], v[168:171], v[4:7], v[0:3]
	v_mfma_f32_16x16x32_bf16 v[136:139], v[164:167], v[12:15], v[136:139]
	v_mfma_f32_16x16x32_bf16 v[140:143], v[172:175], v[12:15], v[140:143]
	ds_read_b64_tr_b16 v[216:217], v103 offset:8192
	ds_read_b64_tr_b16 v[218:219], v103 offset:10240
	ds_read_b64_tr_b16 v[220:221], v133 offset:8192
	ds_read_b64_tr_b16 v[222:223], v133 offset:10240
	ds_read_b64_tr_b16 v[224:225], v134 offset:8192
	ds_read_b64_tr_b16 v[226:227], v134 offset:10240
	ds_read_b64_tr_b16 v[228:229], v135 offset:8192
	ds_read_b64_tr_b16 v[230:231], v135 offset:10240
	v_mfma_f32_16x16x32_bf16 v[176:179], v[160:163], v[8:11], v[0:3]
	v_exp_f32_e32 v136, v136
	v_exp_f32_e32 v137, v137
	v_exp_f32_e32 v138, v138
	v_add_f32_e32 v144, v136, v137
	v_mfma_f32_16x16x32_bf16 v[232:235], v[168:171], v[8:11], v[0:3]
	v_exp_f32_e32 v139, v139
	v_add_f32_e32 v144, v144, v138
	v_exp_f32_e32 v140, v140
	v_add_f32_e32 v144, v144, v139
	v_mfma_f32_16x16x32_bf16 v[176:179], v[164:167], v[16:19], v[176:179]
	v_exp_f32_e32 v141, v141
	v_add_f32_e32 v144, v144, v140
	v_exp_f32_e32 v142, v142
	v_add_f32_e32 v144, v144, v141
	v_cvt_pk_bf16_f32 v136, v136, v137
	v_mfma_f32_16x16x32_bf16 v[232:235], v[172:175], v[16:19], v[232:235]
	v_exp_f32_e32 v143, v143
	v_add_f32_e32 v144, v144, v142
	v_cvt_pk_bf16_f32 v137, v138, v139
	v_cvt_pk_bf16_f32 v138, v140, v141
	v_cvt_pk_bf16_f32 v139, v142, v143
	v_add_f32_e32 v144, v144, v143
	v_add_f32_e32 v131, v131, v144
	s_waitcnt lgkmcnt(0)
	v_mfma_f32_16x16x32_bf16 v[244:247], v[160:163], v[20:23], v[0:3]
	v_exp_f32_e32 v176, v176
	v_exp_f32_e32 v177, v177
	v_mfma_f32_16x16x32_bf16 v[248:251], v[168:171], v[20:23], v[0:3]
	v_exp_f32_e32 v178, v178
	v_add_f32_e32 v144, v176, v177
	v_mfma_f32_16x16x32_bf16 v[244:247], v[164:167], v[24:27], v[244:247]
	v_exp_f32_e32 v179, v179
	v_add_f32_e32 v144, v144, v178
	v_mfma_f32_16x16x32_bf16 v[248:251], v[172:175], v[24:27], v[248:251]
	v_exp_f32_e32 v232, v232
	v_add_f32_e32 v144, v144, v179
	v_mfma_f32_16x16x32_bf16 v[64:67], v[216:219], v[136:139], v[64:67]
	v_exp_f32_e32 v233, v233
	v_add_f32_e32 v144, v144, v232
	v_mfma_f32_16x16x32_bf16 v[60:63], v[220:223], v[136:139], v[60:63]
	v_exp_f32_e32 v234, v234
	v_add_f32_e32 v144, v144, v233
	v_cvt_pk_bf16_f32 v176, v176, v177
	v_mfma_f32_16x16x32_bf16 v[56:59], v[224:227], v[136:139], v[56:59]
	v_exp_f32_e32 v235, v235
	v_add_f32_e32 v144, v144, v234
	v_cvt_pk_bf16_f32 v177, v178, v179
	v_mfma_f32_16x16x32_bf16 v[52:55], v[228:231], v[136:139], v[52:55]
	v_cvt_pk_bf16_f32 v178, v232, v233
	v_cvt_pk_bf16_f32 v179, v234, v235
	v_add_f32_e32 v144, v144, v235
	v_add_f32_e32 v130, v130, v144
	v_mfma_f32_16x16x32_bf16 v[136:139], v[160:163], v[28:31], v[0:3]
	v_exp_f32_e32 v244, v244
	v_exp_f32_e32 v245, v245
	v_mfma_f32_16x16x32_bf16 v[140:143], v[168:171], v[28:31], v[0:3]
	v_exp_f32_e32 v246, v246
	v_add_f32_e32 v144, v244, v245
	v_mfma_f32_16x16x32_bf16 v[136:139], v[164:167], v[32:35], v[136:139]
	v_exp_f32_e32 v247, v247
	v_add_f32_e32 v144, v144, v246
	v_mfma_f32_16x16x32_bf16 v[140:143], v[172:175], v[32:35], v[140:143]
	v_exp_f32_e32 v248, v248
	v_add_f32_e32 v144, v144, v247
	v_mfma_f32_16x16x32_bf16 v[48:51], v[216:219], v[176:179], v[48:51]
	v_exp_f32_e32 v249, v249
	v_add_f32_e32 v144, v144, v248
	v_mfma_f32_16x16x32_bf16 v[44:47], v[220:223], v[176:179], v[44:47]
	v_exp_f32_e32 v250, v250
	v_add_f32_e32 v144, v144, v249
	v_cvt_pk_bf16_f32 v244, v244, v245
	v_mfma_f32_16x16x32_bf16 v[40:43], v[224:227], v[176:179], v[40:43]
	v_exp_f32_e32 v251, v251
	v_add_f32_e32 v144, v144, v250
	v_cvt_pk_bf16_f32 v245, v246, v247
	v_mfma_f32_16x16x32_bf16 v[36:39], v[228:231], v[176:179], v[36:39]
	v_cvt_pk_bf16_f32 v246, v248, v249
	v_cvt_pk_bf16_f32 v247, v250, v251
	v_add_f32_e32 v144, v144, v251
	v_add_f32_e32 v129, v129, v144
	ds_read_b64_tr_b16 v[160:161], v103 offset:12288
	ds_read_b64_tr_b16 v[162:163], v103 offset:14336
	ds_read_b64_tr_b16 v[164:165], v133 offset:12288
	ds_read_b64_tr_b16 v[166:167], v133 offset:14336
	ds_read_b64_tr_b16 v[168:169], v134 offset:12288
	ds_read_b64_tr_b16 v[170:171], v134 offset:14336
	ds_read_b64_tr_b16 v[172:173], v135 offset:12288
	ds_read_b64_tr_b16 v[174:175], v135 offset:14336
	v_mfma_f32_16x16x32_bf16 v[176:179], v[104:107], v[4:7], v[0:3]
	v_exp_f32_e32 v136, v136
	v_exp_f32_e32 v137, v137
	v_mfma_f32_16x16x32_bf16 v[232:235], v[112:115], v[4:7], v[0:3]
	v_exp_f32_e32 v138, v138
	v_add_f32_e32 v144, v136, v137
	v_mfma_f32_16x16x32_bf16 v[176:179], v[108:111], v[12:15], v[176:179]
	v_exp_f32_e32 v139, v139
	v_add_f32_e32 v144, v144, v138
	v_mfma_f32_16x16x32_bf16 v[232:235], v[116:119], v[12:15], v[232:235]
	v_exp_f32_e32 v140, v140
	v_add_f32_e32 v144, v144, v139
	v_mfma_f32_16x16x32_bf16 v[72:75], v[216:219], v[244:247], v[72:75]
	v_exp_f32_e32 v141, v141
	v_add_f32_e32 v144, v144, v140
	v_mfma_f32_16x16x32_bf16 v[84:87], v[220:223], v[244:247], v[84:87]
	v_exp_f32_e32 v142, v142
	v_add_f32_e32 v144, v144, v141
	v_cvt_pk_bf16_f32 v136, v136, v137
	v_mfma_f32_16x16x32_bf16 v[88:91], v[224:227], v[244:247], v[88:91]
	v_exp_f32_e32 v143, v143
	v_add_f32_e32 v144, v144, v142
	v_cvt_pk_bf16_f32 v137, v138, v139
	v_mfma_f32_16x16x32_bf16 v[96:99], v[228:231], v[244:247], v[96:99]
	v_cvt_pk_bf16_f32 v138, v140, v141
	v_cvt_pk_bf16_f32 v139, v142, v143
	v_add_f32_e32 v144, v144, v143
	v_add_f32_e32 v128, v128, v144
	v_mfma_f32_16x16x32_bf16 v[244:247], v[104:107], v[8:11], v[0:3]
	v_exp_f32_e32 v176, v176
	v_exp_f32_e32 v177, v177
	v_mfma_f32_16x16x32_bf16 v[248:251], v[112:115], v[8:11], v[0:3]
	v_exp_f32_e32 v178, v178
	v_add_f32_e32 v144, v176, v177
	v_mfma_f32_16x16x32_bf16 v[244:247], v[108:111], v[16:19], v[244:247]
	v_exp_f32_e32 v179, v179
	v_add_f32_e32 v144, v144, v178
	v_mfma_f32_16x16x32_bf16 v[248:251], v[116:119], v[16:19], v[248:251]
	v_exp_f32_e32 v232, v232
	v_add_f32_e32 v144, v144, v179
	v_mfma_f32_16x16x32_bf16 v[68:71], v[216:219], v[136:139], v[68:71]
	v_exp_f32_e32 v233, v233
	v_add_f32_e32 v144, v144, v232
	v_mfma_f32_16x16x32_bf16 v[76:79], v[220:223], v[136:139], v[76:79]
	v_exp_f32_e32 v234, v234
	v_add_f32_e32 v144, v144, v233
	v_cvt_pk_bf16_f32 v176, v176, v177
	v_mfma_f32_16x16x32_bf16 v[80:83], v[224:227], v[136:139], v[80:83]
	v_exp_f32_e32 v235, v235
	v_add_f32_e32 v144, v144, v234
	v_cvt_pk_bf16_f32 v177, v178, v179
	v_mfma_f32_16x16x32_bf16 v[92:95], v[228:231], v[136:139], v[92:95]
	v_cvt_pk_bf16_f32 v178, v232, v233
	v_cvt_pk_bf16_f32 v179, v234, v235
	v_add_f32_e32 v144, v144, v235
	v_add_f32_e32 v131, v131, v144
	s_waitcnt lgkmcnt(0)
; #define LAS __attribute__((address_space(3)))
; __device__ __forceinline__ s16x4 vtr(const LAS unsigned char* p) { return __builtin_bit_cast(s16x4, __builtin_amdgcn_ds_read_tr16_b64_v4i16((LAS v4i16_t*)p)); }
; __device__ __forceinline__ bf16x8 cat8(s16x4 a, s16x4 b) { return (bf16x8){a[0], a[1], a[2], a[3], b[0], b[1], b[2], b[3]}; }
;     ...
;         for (int kb = 0; kb < 4; ++kb) {
;             const bf16x8 kf0 = *(const LAS bf16x8*)(kb0 + (16 * kb) * 128 + kx0), kf1 = *(const LAS bf16x8*)(kb0 + (16 * kb) * 128 + kx1);
; #pragma unroll
;             for (int gi = 0; gi < GPB; ++gi) { S[gi][kb] = __builtin_amdgcn_mfma_f32_16x16x32_bf16(kf0, qf[GPB * gh + gi][0], cinit, 0, 0, 0);
;                 S[gi][kb] = __builtin_amdgcn_mfma_f32_16x16x32_bf16(kf1, qf[GPB * gh + gi][1], S[gi][kb], 0, 0, 0); } }
;         bf16x8 pf[GPB][2];
; #pragma unroll
;         for (int gi = 0; gi < GPB; ++gi) {
;             if (MASK) {
; #pragma unroll
;                 for (int kb = 0; kb < 4; ++kb)
; #pragma unroll
;                     for (int i = 0; i < 4; ++i) { const int rel = rel0 + 16 * kb + 4 * g + i; S[gi][kb][i] = ((unsigned)(rel + 128) > 256u) ? NEGBIG : S[gi][kb][i]; }
;             }
;             ls[GPB * gh + gi] += exp_step<4>(S[gi]);
;             pf[gi][0] = pack8(S[gi][0], S[gi][1]); pf[gi][1] = pack8(S[gi][2], S[gi][3]);
;         }
; #pragma unroll
;         for (int kc = 0; kc < 2; ++kc)
; #pragma unroll
;             for (int db = 0; db < 4; ++db) {
;                 const LAS unsigned char* va = vrow + ((db ^ swz) << 5) + (32 * kc) * 128;
;                 const bf16x8 vf = cat8(vtr(va), vtr(va + 16 * 128));
; #pragma unroll
;                 for (int gi = 0; gi < GPB; ++gi) O[GPB * gh + gi][db] = __builtin_amdgcn_mfma_f32_16x16x32_bf16(vf, pf[gi][kc], O[GPB * gh + gi][db], 0, 0, 0);
;             }
; __device__ __forceinline__ void swa_phase(LAS unsigned char* lds, const bf16_t* Q, const bf16_t* K, const bf16_t* V, bf16_t* Ob, const float* sink, float negb) {
;     ...
;         for (int t = 0; t < 4; ++t) {
;             dma_tile<1>(lds + ((t + 3) & 3) * SW_BUF, K, V, SW_ROW0(t + 3), 256, dl, w);
;             const LAS unsigned char* buf = lds + (t & 3) * SW_BUF;
;             full_tile<0, 2, 2>(O, ls, qf, negb, buf, buf + 8192, lane, 0);
;             ring_wait<2>();
	v_mfma_f32_16x16x32_bf16 v[136:139], v[104:107], v[20:23], v[0:3]
	v_exp_f32_e32 v244, v244
	v_exp_f32_e32 v245, v245
	v_mfma_f32_16x16x32_bf16 v[140:143], v[112:115], v[20:23], v[0:3]
	v_exp_f32_e32 v246, v246
	v_add_f32_e32 v144, v244, v245
	v_mfma_f32_16x16x32_bf16 v[136:139], v[108:111], v[24:27], v[136:139]
	v_exp_f32_e32 v247, v247
	v_add_f32_e32 v144, v144, v246
	v_mfma_f32_16x16x32_bf16 v[140:143], v[116:119], v[24:27], v[140:143]
	v_exp_f32_e32 v248, v248
	v_add_f32_e32 v144, v144, v247
	v_mfma_f32_16x16x32_bf16 v[64:67], v[160:163], v[176:179], v[64:67]
	v_exp_f32_e32 v249, v249
	v_add_f32_e32 v144, v144, v248
	v_mfma_f32_16x16x32_bf16 v[60:63], v[164:167], v[176:179], v[60:63]
	v_exp_f32_e32 v250, v250
	v_add_f32_e32 v144, v144, v249
	v_cvt_pk_bf16_f32 v244, v244, v245
	v_mfma_f32_16x16x32_bf16 v[56:59], v[168:171], v[176:179], v[56:59]
	v_exp_f32_e32 v251, v251
	v_add_f32_e32 v144, v144, v250
	v_cvt_pk_bf16_f32 v245, v246, v247
	v_mfma_f32_16x16x32_bf16 v[52:55], v[172:175], v[176:179], v[52:55]
	v_cvt_pk_bf16_f32 v246, v248, v249
	v_cvt_pk_bf16_f32 v247, v250, v251
	v_add_f32_e32 v144, v144, v251
	v_add_f32_e32 v130, v130, v144
	v_mfma_f32_16x16x32_bf16 v[176:179], v[104:107], v[28:31], v[0:3]
	v_exp_f32_e32 v136, v136
	v_exp_f32_e32 v137, v137
	v_mfma_f32_16x16x32_bf16 v[232:235], v[112:115], v[28:31], v[0:3]
	v_exp_f32_e32 v138, v138
	v_add_f32_e32 v144, v136, v137
	v_mfma_f32_16x16x32_bf16 v[176:179], v[108:111], v[32:35], v[176:179]
	v_exp_f32_e32 v139, v139
	v_add_f32_e32 v144, v144, v138
	v_mfma_f32_16x16x32_bf16 v[232:235], v[116:119], v[32:35], v[232:235]
	v_exp_f32_e32 v140, v140
	v_add_f32_e32 v144, v144, v139
	v_mfma_f32_16x16x32_bf16 v[48:51], v[160:163], v[244:247], v[48:51]
	v_exp_f32_e32 v141, v141
	v_add_f32_e32 v144, v144, v140
	v_mfma_f32_16x16x32_bf16 v[44:47], v[164:167], v[244:247], v[44:47]
	v_exp_f32_e32 v142, v142
	v_add_f32_e32 v144, v144, v141
	v_cvt_pk_bf16_f32 v136, v136, v137
	v_mfma_f32_16x16x32_bf16 v[40:43], v[168:171], v[244:247], v[40:43]
	v_exp_f32_e32 v143, v143
	v_add_f32_e32 v144, v144, v142
	v_cvt_pk_bf16_f32 v137, v138, v139
	v_mfma_f32_16x16x32_bf16 v[36:39], v[172:175], v[244:247], v[36:39]
	v_cvt_pk_bf16_f32 v138, v140, v141
	v_cvt_pk_bf16_f32 v139, v142, v143
	v_add_f32_e32 v144, v144, v143
	v_add_f32_e32 v129, v129, v144
	v_mfma_f32_16x16x32_bf16 v[72:75], v[160:163], v[136:139], v[72:75]
	v_exp_f32_e32 v176, v176
	v_exp_f32_e32 v177, v177
	v_exp_f32_e32 v178, v178
	v_add_f32_e32 v144, v176, v177
	v_mfma_f32_16x16x32_bf16 v[84:87], v[164:167], v[136:139], v[84:87]
	v_exp_f32_e32 v179, v179
	v_add_f32_e32 v144, v144, v178
	v_exp_f32_e32 v232, v232
	v_add_f32_e32 v144, v144, v179
	v_mfma_f32_16x16x32_bf16 v[88:91], v[168:171], v[136:139], v[88:91]
	v_exp_f32_e32 v233, v233
	v_add_f32_e32 v144, v144, v232
	v_exp_f32_e32 v234, v234
	v_add_f32_e32 v144, v144, v233
	v_cvt_pk_bf16_f32 v176, v176, v177
	v_mfma_f32_16x16x32_bf16 v[96:99], v[172:175], v[136:139], v[96:99]
	v_exp_f32_e32 v235, v235
	v_add_f32_e32 v144, v144, v234
	v_cvt_pk_bf16_f32 v177, v178, v179
	v_cvt_pk_bf16_f32 v178, v232, v233
	v_cvt_pk_bf16_f32 v179, v234, v235
	v_add_f32_e32 v144, v144, v235
	v_add_f32_e32 v128, v128, v144
	v_mfma_f32_16x16x32_bf16 v[68:71], v[160:163], v[176:179], v[68:71]
	v_mfma_f32_16x16x32_bf16 v[76:79], v[164:167], v[176:179], v[76:79]
	v_mfma_f32_16x16x32_bf16 v[80:83], v[168:171], v[176:179], v[80:83]
	v_mfma_f32_16x16x32_bf16 v[92:95], v[172:175], v[176:179], v[92:95]
	s_waitcnt vmcnt(4)
	s_barrier
	s_cmp_lt_u32 s6, s46
	s_cselect_b32 s11, s8, 0
	s_cselect_b32 s10, s7, s82
	s_lshl_b64 s[10:11], s[10:11], 9
	s_add_u32 s12, s67, s10
	s_addc_u32 s13, s4, s11
	s_add_u32 s10, s5, s10
	s_addc_u32 s11, s58, s11
	s_add_i32 s9, s40, s1
	s_mov_b32 s15, m0
	s_mov_b32 m0, s9
	s_nop 0
	global_load_lds_dwordx4 v212, s[12:13]
	s_mov_b32 m0, s15
	s_add_i32 s14, s9, 0x2000
	s_mov_b32 s9, m0
	s_mov_b32 m0, s14
	s_nop 0
	global_load_lds_dwordx4 v213, s[10:11]
	s_mov_b32 m0, s9
	s_add_i32 s34, s1, 0x4000
	v_add_u32_e32 v100, s34, v191
	v_add3_u32 v135, s34, v203, v198
	v_add_u32_e32 v102, v100, v193
	v_add_u32_e32 v100, v100, v192
	ds_read_b128 v[160:163], v100
	ds_read_b128 v[164:167], v102
	ds_read_b128 v[168:171], v100 offset:2048
	ds_read_b128 v[172:175], v102 offset:2048
	ds_read_b128 v[104:107], v100 offset:4096
	ds_read_b128 v[108:111], v102 offset:4096
	ds_read_b128 v[112:115], v100 offset:6144
	ds_read_b128 v[116:119], v102 offset:6144
	v_add_u32_e32 v103, v135, v199
	v_add_u32_e32 v133, v135, v200
	v_add_u32_e32 v134, v135, v201
	v_add_u32_e32 v135, v135, v202
	s_waitcnt lgkmcnt(4)
	v_mfma_f32_16x16x32_bf16 v[136:139], v[160:163], v[4:7], v[0:3]
	v_mfma_f32_16x16x32_bf16 v[140:143], v[168:171], v[4:7], v[0:3]
	v_mfma_f32_16x16x32_bf16 v[136:139], v[164:167], v[12:15], v[136:139]
	v_mfma_f32_16x16x32_bf16 v[140:143], v[172:175], v[12:15], v[140:143]
	ds_read_b64_tr_b16 v[216:217], v103 offset:8192
	ds_read_b64_tr_b16 v[218:219], v103 offset:10240
	ds_read_b64_tr_b16 v[220:221], v133 offset:8192
	ds_read_b64_tr_b16 v[222:223], v133 offset:10240
	ds_read_b64_tr_b16 v[224:225], v134 offset:8192
	ds_read_b64_tr_b16 v[226:227], v134 offset:10240
	ds_read_b64_tr_b16 v[228:229], v135 offset:8192
	ds_read_b64_tr_b16 v[230:231], v135 offset:10240
	v_mfma_f32_16x16x32_bf16 v[176:179], v[160:163], v[8:11], v[0:3]
	v_exp_f32_e32 v136, v136
	v_exp_f32_e32 v137, v137
	v_exp_f32_e32 v138, v138
	v_add_f32_e32 v144, v136, v137
	v_mfma_f32_16x16x32_bf16 v[232:235], v[168:171], v[8:11], v[0:3]
	v_exp_f32_e32 v139, v139
	v_add_f32_e32 v144, v144, v138
	v_exp_f32_e32 v140, v140
	v_add_f32_e32 v144, v144, v139
	v_mfma_f32_16x16x32_bf16 v[176:179], v[164:167], v[16:19], v[176:179]
	v_exp_f32_e32 v141, v141
	v_add_f32_e32 v144, v144, v140
	v_exp_f32_e32 v142, v142
	v_add_f32_e32 v144, v144, v141
	v_cvt_pk_bf16_f32 v136, v136, v137
	v_mfma_f32_16x16x32_bf16 v[232:235], v[172:175], v[16:19], v[232:235]
	v_exp_f32_e32 v143, v143
	v_add_f32_e32 v144, v144, v142
	v_cvt_pk_bf16_f32 v137, v138, v139
	v_cvt_pk_bf16_f32 v138, v140, v141
	v_cvt_pk_bf16_f32 v139, v142, v143
	v_add_f32_e32 v144, v144, v143
	v_add_f32_e32 v131, v131, v144
	s_waitcnt lgkmcnt(0)
; #define LAS __attribute__((address_space(3)))
; __device__ __forceinline__ s16x4 vtr(const LAS unsigned char* p) { return __builtin_bit_cast(s16x4, __builtin_amdgcn_ds_read_tr16_b64_v4i16((LAS v4i16_t*)p)); }
; __device__ __forceinline__ bf16x8 cat8(s16x4 a, s16x4 b) { return (bf16x8){a[0], a[1], a[2], a[3], b[0], b[1], b[2], b[3]}; }
; __device__ __forceinline__ bf16x8 pack8(const f32x4& a, const f32x4& b) { u32x4 w; w.x = pkbf(a[0], a[1]); w.y = pkbf(a[2], a[3]); w.z = pkbf(b[0], b[1]); w.w = pkbf(b[2], b[3]); return __builtin_bit_cast(bf16x8, w); }
;     ...
;     for (int gh = 0; gh < 4 / GPB; ++gh) {
;         f32x4 S[GPB][4];
; #pragma unroll
;         for (int kb = 0; kb < 4; ++kb) {
;             const bf16x8 kf0 = *(const LAS bf16x8*)(kb0 + (16 * kb) * 128 + kx0), kf1 = *(const LAS bf16x8*)(kb0 + (16 * kb) * 128 + kx1);
; #pragma unroll
;             for (int gi = 0; gi < GPB; ++gi) { S[gi][kb] = __builtin_amdgcn_mfma_f32_16x16x32_bf16(kf0, qf[GPB * gh + gi][0], cinit, 0, 0, 0);
;                 S[gi][kb] = __builtin_amdgcn_mfma_f32_16x16x32_bf16(kf1, qf[GPB * gh + gi][1], S[gi][kb], 0, 0, 0); } }
;         bf16x8 pf[GPB][2];
; #pragma unroll
;         for (int gi = 0; gi < GPB; ++gi) {
;             if (MASK) {
; #pragma unroll
;                 for (int kb = 0; kb < 4; ++kb)
; #pragma unroll
;                     for (int i = 0; i < 4; ++i) { const int rel = rel0 + 16 * kb + 4 * g + i; S[gi][kb][i] = ((unsigned)(rel + 128) > 256u) ? NEGBIG : S[gi][kb][i]; }
;             }
;             ls[GPB * gh + gi] += exp_step<4>(S[gi]);
;             pf[gi][0] = pack8(S[gi][0], S[gi][1]); pf[gi][1] = pack8(S[gi][2], S[gi][3]);
;         }
; #pragma unroll
;         for (int kc = 0; kc < 2; ++kc)
; #pragma unroll
;             for (int db = 0; db < 4; ++db) {
;                 const LAS unsigned char* va = vrow + ((db ^ swz) << 5) + (32 * kc) * 128;
;                 const bf16x8 vf = cat8(vtr(va), vtr(va + 16 * 128));
; #pragma unroll
;                 for (int gi = 0; gi < GPB; ++gi) O[GPB * gh + gi][db] = __builtin_amdgcn_mfma_f32_16x16x32_bf16(vf, pf[gi][kc], O[GPB * gh + gi][db], 0, 0, 0);
;             }
	v_mfma_f32_16x16x32_bf16 v[244:247], v[160:163], v[20:23], v[0:3]
	v_exp_f32_e32 v176, v176
	v_exp_f32_e32 v177, v177
	v_mfma_f32_16x16x32_bf16 v[248:251], v[168:171], v[20:23], v[0:3]
	v_exp_f32_e32 v178, v178
	v_add_f32_e32 v144, v176, v177
	v_mfma_f32_16x16x32_bf16 v[244:247], v[164:167], v[24:27], v[244:247]
	v_exp_f32_e32 v179, v179
	v_add_f32_e32 v144, v144, v178
	v_mfma_f32_16x16x32_bf16 v[248:251], v[172:175], v[24:27], v[248:251]
	v_exp_f32_e32 v232, v232
	v_add_f32_e32 v144, v144, v179
	v_mfma_f32_16x16x32_bf16 v[64:67], v[216:219], v[136:139], v[64:67]
	v_exp_f32_e32 v233, v233
	v_add_f32_e32 v144, v144, v232
	v_mfma_f32_16x16x32_bf16 v[60:63], v[220:223], v[136:139], v[60:63]
	v_exp_f32_e32 v234, v234
	v_add_f32_e32 v144, v144, v233
	v_cvt_pk_bf16_f32 v176, v176, v177
	v_mfma_f32_16x16x32_bf16 v[56:59], v[224:227], v[136:139], v[56:59]
	v_exp_f32_e32 v235, v235
	v_add_f32_e32 v144, v144, v234
	v_cvt_pk_bf16_f32 v177, v178, v179
	v_mfma_f32_16x16x32_bf16 v[52:55], v[228:231], v[136:139], v[52:55]
	v_cvt_pk_bf16_f32 v178, v232, v233
	v_cvt_pk_bf16_f32 v179, v234, v235
	v_add_f32_e32 v144, v144, v235
	v_add_f32_e32 v130, v130, v144
	v_mfma_f32_16x16x32_bf16 v[136:139], v[160:163], v[28:31], v[0:3]
	v_exp_f32_e32 v244, v244
	v_exp_f32_e32 v245, v245
	v_mfma_f32_16x16x32_bf16 v[140:143], v[168:171], v[28:31], v[0:3]
	v_exp_f32_e32 v246, v246
	v_add_f32_e32 v144, v244, v245
	v_mfma_f32_16x16x32_bf16 v[136:139], v[164:167], v[32:35], v[136:139]
	v_exp_f32_e32 v247, v247
	v_add_f32_e32 v144, v144, v246
	v_mfma_f32_16x16x32_bf16 v[140:143], v[172:175], v[32:35], v[140:143]
	v_exp_f32_e32 v248, v248
	v_add_f32_e32 v144, v144, v247
	v_mfma_f32_16x16x32_bf16 v[48:51], v[216:219], v[176:179], v[48:51]
	v_exp_f32_e32 v249, v249
	v_add_f32_e32 v144, v144, v248
	v_mfma_f32_16x16x32_bf16 v[44:47], v[220:223], v[176:179], v[44:47]
	v_exp_f32_e32 v250, v250
	v_add_f32_e32 v144, v144, v249
	v_cvt_pk_bf16_f32 v244, v244, v245
	v_mfma_f32_16x16x32_bf16 v[40:43], v[224:227], v[176:179], v[40:43]
	v_exp_f32_e32 v251, v251
	v_add_f32_e32 v144, v144, v250
	v_cvt_pk_bf16_f32 v245, v246, v247
	v_mfma_f32_16x16x32_bf16 v[36:39], v[228:231], v[176:179], v[36:39]
	v_cvt_pk_bf16_f32 v246, v248, v249
	v_cvt_pk_bf16_f32 v247, v250, v251
	v_add_f32_e32 v144, v144, v251
	v_add_f32_e32 v129, v129, v144
	ds_read_b64_tr_b16 v[160:161], v103 offset:12288
	ds_read_b64_tr_b16 v[162:163], v103 offset:14336
	ds_read_b64_tr_b16 v[164:165], v133 offset:12288
	ds_read_b64_tr_b16 v[166:167], v133 offset:14336
	ds_read_b64_tr_b16 v[168:169], v134 offset:12288
	ds_read_b64_tr_b16 v[170:171], v134 offset:14336
	ds_read_b64_tr_b16 v[172:173], v135 offset:12288
	ds_read_b64_tr_b16 v[174:175], v135 offset:14336
	v_mfma_f32_16x16x32_bf16 v[176:179], v[104:107], v[4:7], v[0:3]
	v_exp_f32_e32 v136, v136
	v_exp_f32_e32 v137, v137
	v_mfma_f32_16x16x32_bf16 v[232:235], v[112:115], v[4:7], v[0:3]
	v_exp_f32_e32 v138, v138
	v_add_f32_e32 v144, v136, v137
	v_mfma_f32_16x16x32_bf16 v[176:179], v[108:111], v[12:15], v[176:179]
	v_exp_f32_e32 v139, v139
	v_add_f32_e32 v144, v144, v138
	v_mfma_f32_16x16x32_bf16 v[232:235], v[116:119], v[12:15], v[232:235]
	v_exp_f32_e32 v140, v140
	v_add_f32_e32 v144, v144, v139
	v_mfma_f32_16x16x32_bf16 v[72:75], v[216:219], v[244:247], v[72:75]
	v_exp_f32_e32 v141, v141
	v_add_f32_e32 v144, v144, v140
	v_mfma_f32_16x16x32_bf16 v[84:87], v[220:223], v[244:247], v[84:87]
	v_exp_f32_e32 v142, v142
	v_add_f32_e32 v144, v144, v141
	v_cvt_pk_bf16_f32 v136, v136, v137
	v_mfma_f32_16x16x32_bf16 v[88:91], v[224:227], v[244:247], v[88:91]
	v_exp_f32_e32 v143, v143
	v_add_f32_e32 v144, v144, v142
	v_cvt_pk_bf16_f32 v137, v138, v139
	v_mfma_f32_16x16x32_bf16 v[96:99], v[228:231], v[244:247], v[96:99]
	v_cvt_pk_bf16_f32 v138, v140, v141
	v_cvt_pk_bf16_f32 v139, v142, v143
	v_add_f32_e32 v144, v144, v143
	v_add_f32_e32 v128, v128, v144
	v_mfma_f32_16x16x32_bf16 v[244:247], v[104:107], v[8:11], v[0:3]
	v_exp_f32_e32 v176, v176
	v_exp_f32_e32 v177, v177
	v_mfma_f32_16x16x32_bf16 v[248:251], v[112:115], v[8:11], v[0:3]
	v_exp_f32_e32 v178, v178
	v_add_f32_e32 v144, v176, v177
	v_mfma_f32_16x16x32_bf16 v[244:247], v[108:111], v[16:19], v[244:247]
	v_exp_f32_e32 v179, v179
	v_add_f32_e32 v144, v144, v178
	v_mfma_f32_16x16x32_bf16 v[248:251], v[116:119], v[16:19], v[248:251]
	v_exp_f32_e32 v232, v232
	v_add_f32_e32 v144, v144, v179
	v_mfma_f32_16x16x32_bf16 v[68:71], v[216:219], v[136:139], v[68:71]
	v_exp_f32_e32 v233, v233
	v_add_f32_e32 v144, v144, v232
	v_mfma_f32_16x16x32_bf16 v[76:79], v[220:223], v[136:139], v[76:79]
	v_exp_f32_e32 v234, v234
	v_add_f32_e32 v144, v144, v233
	v_cvt_pk_bf16_f32 v176, v176, v177
	v_mfma_f32_16x16x32_bf16 v[80:83], v[224:227], v[136:139], v[80:83]
	v_exp_f32_e32 v235, v235
	v_add_f32_e32 v144, v144, v234
	v_cvt_pk_bf16_f32 v177, v178, v179
	v_mfma_f32_16x16x32_bf16 v[92:95], v[228:231], v[136:139], v[92:95]
	v_cvt_pk_bf16_f32 v178, v232, v233
	v_cvt_pk_bf16_f32 v179, v234, v235
	v_add_f32_e32 v144, v144, v235
	v_add_f32_e32 v131, v131, v144
	s_waitcnt lgkmcnt(0)
; #define LAS __attribute__((address_space(3)))
; __device__ __forceinline__ s16x4 vtr(const LAS unsigned char* p) { return __builtin_bit_cast(s16x4, __builtin_amdgcn_ds_read_tr16_b64_v4i16((LAS v4i16_t*)p)); }
; __device__ __forceinline__ bf16x8 cat8(s16x4 a, s16x4 b) { return (bf16x8){a[0], a[1], a[2], a[3], b[0], b[1], b[2], b[3]}; }
;     ...
;         for (int kb = 0; kb < 4; ++kb) {
;             const bf16x8 kf0 = *(const LAS bf16x8*)(kb0 + (16 * kb) * 128 + kx0), kf1 = *(const LAS bf16x8*)(kb0 + (16 * kb) * 128 + kx1);
; #pragma unroll
;             for (int gi = 0; gi < GPB; ++gi) { S[gi][kb] = __builtin_amdgcn_mfma_f32_16x16x32_bf16(kf0, qf[GPB * gh + gi][0], cinit, 0, 0, 0);
;                 S[gi][kb] = __builtin_amdgcn_mfma_f32_16x16x32_bf16(kf1, qf[GPB * gh + gi][1], S[gi][kb], 0, 0, 0); } }
;         bf16x8 pf[GPB][2];
; #pragma unroll
;         for (int gi = 0; gi < GPB; ++gi) {
;             if (MASK) {
; #pragma unroll
;                 for (int kb = 0; kb < 4; ++kb)
; #pragma unroll
;                     for (int i = 0; i < 4; ++i) { const int rel = rel0 + 16 * kb + 4 * g + i; S[gi][kb][i] = ((unsigned)(rel + 128) > 256u) ? NEGBIG : S[gi][kb][i]; }
;             }
;             ls[GPB * gh + gi] += exp_step<4>(S[gi]);
;             pf[gi][0] = pack8(S[gi][0], S[gi][1]); pf[gi][1] = pack8(S[gi][2], S[gi][3]);
;         }
; #pragma unroll
;         for (int kc = 0; kc < 2; ++kc)
; #pragma unroll
;             for (int db = 0; db < 4; ++db) {
;                 const LAS unsigned char* va = vrow + ((db ^ swz) << 5) + (32 * kc) * 128;
;                 const bf16x8 vf = cat8(vtr(va), vtr(va + 16 * 128));
; #pragma unroll
;                 for (int gi = 0; gi < GPB; ++gi) O[GPB * gh + gi][db] = __builtin_amdgcn_mfma_f32_16x16x32_bf16(vf, pf[gi][kc], O[GPB * gh + gi][db], 0, 0, 0);
;             }
; __device__ __forceinline__ void swa_phase(LAS unsigned char* lds, const bf16_t* Q, const bf16_t* K, const bf16_t* V, bf16_t* Ob, const float* sink, float negb) {
;     ...
;         for (int t = 0; t < 4; ++t) {
;             dma_tile<1>(lds + ((t + 3) & 3) * SW_BUF, K, V, SW_ROW0(t + 3), 256, dl, w);
;             const LAS unsigned char* buf = lds + (t & 3) * SW_BUF;
;             full_tile<0, 2, 2>(O, ls, qf, negb, buf, buf + 8192, lane, 0);
;             ring_wait<2>();
	v_mfma_f32_16x16x32_bf16 v[136:139], v[104:107], v[20:23], v[0:3]
	v_exp_f32_e32 v244, v244
	v_exp_f32_e32 v245, v245
	v_mfma_f32_16x16x32_bf16 v[140:143], v[112:115], v[20:23], v[0:3]
	v_exp_f32_e32 v246, v246
	v_add_f32_e32 v144, v244, v245
	v_mfma_f32_16x16x32_bf16 v[136:139], v[108:111], v[24:27], v[136:139]
	v_exp_f32_e32 v247, v247
	v_add_f32_e32 v144, v144, v246
	v_mfma_f32_16x16x32_bf16 v[140:143], v[116:119], v[24:27], v[140:143]
	v_exp_f32_e32 v248, v248
	v_add_f32_e32 v144, v144, v247
	v_mfma_f32_16x16x32_bf16 v[64:67], v[160:163], v[176:179], v[64:67]
	v_exp_f32_e32 v249, v249
	v_add_f32_e32 v144, v144, v248
	v_mfma_f32_16x16x32_bf16 v[60:63], v[164:167], v[176:179], v[60:63]
	v_exp_f32_e32 v250, v250
	v_add_f32_e32 v144, v144, v249
	v_cvt_pk_bf16_f32 v244, v244, v245
	v_mfma_f32_16x16x32_bf16 v[56:59], v[168:171], v[176:179], v[56:59]
	v_exp_f32_e32 v251, v251
	v_add_f32_e32 v144, v144, v250
	v_cvt_pk_bf16_f32 v245, v246, v247
	v_mfma_f32_16x16x32_bf16 v[52:55], v[172:175], v[176:179], v[52:55]
	v_cvt_pk_bf16_f32 v246, v248, v249
	v_cvt_pk_bf16_f32 v247, v250, v251
	v_add_f32_e32 v144, v144, v251
	v_add_f32_e32 v130, v130, v144
	v_mfma_f32_16x16x32_bf16 v[176:179], v[104:107], v[28:31], v[0:3]
	v_exp_f32_e32 v136, v136
	v_exp_f32_e32 v137, v137
	v_mfma_f32_16x16x32_bf16 v[232:235], v[112:115], v[28:31], v[0:3]
	v_exp_f32_e32 v138, v138
	v_add_f32_e32 v144, v136, v137
	v_mfma_f32_16x16x32_bf16 v[176:179], v[108:111], v[32:35], v[176:179]
	v_exp_f32_e32 v139, v139
	v_add_f32_e32 v144, v144, v138
	v_mfma_f32_16x16x32_bf16 v[232:235], v[116:119], v[32:35], v[232:235]
	v_exp_f32_e32 v140, v140
	v_add_f32_e32 v144, v144, v139
	v_mfma_f32_16x16x32_bf16 v[48:51], v[160:163], v[244:247], v[48:51]
	v_exp_f32_e32 v141, v141
	v_add_f32_e32 v144, v144, v140
	v_mfma_f32_16x16x32_bf16 v[44:47], v[164:167], v[244:247], v[44:47]
	v_exp_f32_e32 v142, v142
	v_add_f32_e32 v144, v144, v141
	v_cvt_pk_bf16_f32 v136, v136, v137
	v_mfma_f32_16x16x32_bf16 v[40:43], v[168:171], v[244:247], v[40:43]
	v_exp_f32_e32 v143, v143
	v_add_f32_e32 v144, v144, v142
	v_cvt_pk_bf16_f32 v137, v138, v139
	v_mfma_f32_16x16x32_bf16 v[36:39], v[172:175], v[244:247], v[36:39]
	v_cvt_pk_bf16_f32 v138, v140, v141
	v_cvt_pk_bf16_f32 v139, v142, v143
	v_add_f32_e32 v144, v144, v143
	v_add_f32_e32 v129, v129, v144
	v_mfma_f32_16x16x32_bf16 v[72:75], v[160:163], v[136:139], v[72:75]
	v_exp_f32_e32 v176, v176
	v_exp_f32_e32 v177, v177
	v_exp_f32_e32 v178, v178
	v_add_f32_e32 v144, v176, v177
	v_mfma_f32_16x16x32_bf16 v[84:87], v[164:167], v[136:139], v[84:87]
	v_exp_f32_e32 v179, v179
	v_add_f32_e32 v144, v144, v178
	v_exp_f32_e32 v232, v232
	v_add_f32_e32 v144, v144, v179
	v_mfma_f32_16x16x32_bf16 v[88:91], v[168:171], v[136:139], v[88:91]
	v_exp_f32_e32 v233, v233
	v_add_f32_e32 v144, v144, v232
	v_exp_f32_e32 v234, v234
	v_add_f32_e32 v144, v144, v233
	v_cvt_pk_bf16_f32 v176, v176, v177
	v_mfma_f32_16x16x32_bf16 v[96:99], v[172:175], v[136:139], v[96:99]
	v_exp_f32_e32 v235, v235
	v_add_f32_e32 v144, v144, v234
	v_cvt_pk_bf16_f32 v177, v178, v179
	v_cvt_pk_bf16_f32 v178, v232, v233
	v_cvt_pk_bf16_f32 v179, v234, v235
	v_add_f32_e32 v144, v144, v235
	v_add_f32_e32 v128, v128, v144
	v_mfma_f32_16x16x32_bf16 v[68:71], v[160:163], v[176:179], v[68:71]
	v_mfma_f32_16x16x32_bf16 v[76:79], v[164:167], v[176:179], v[76:79]
	v_mfma_f32_16x16x32_bf16 v[80:83], v[168:171], v[176:179], v[80:83]
	v_mfma_f32_16x16x32_bf16 v[92:95], v[172:175], v[176:179], v[92:95]
	s_addk_i32 s1, 0x4000
	s_add_u32 s7, s7, 64
	s_addc_u32 s8, s8, 0
	s_add_i32 s6, s6, 1
	s_waitcnt vmcnt(4)
	s_barrier
	s_cmp_lt_u32 s6, s46
	s_cselect_b32 s11, s8, 0
	s_cselect_b32 s10, s7, s82
	s_lshl_b64 s[10:11], s[10:11], 9
	s_add_u32 s12, s67, s10
	s_addc_u32 s13, s4, s11
	s_add_u32 s10, s5, s10
	s_addc_u32 s11, s58, s11
	s_add_i32 s9, s40, s1
	s_mov_b32 s15, m0
	s_mov_b32 m0, s9
	s_nop 0
	global_load_lds_dwordx4 v212, s[12:13]
	s_mov_b32 m0, s15
	s_add_i32 s14, s9, 0x2000
	s_mov_b32 s9, m0
	s_mov_b32 m0, s14
	s_nop 0
	global_load_lds_dwordx4 v213, s[10:11]
	s_mov_b32 m0, s9
	s_add_i32 s34, s1, 0x4000
	v_add_u32_e32 v100, s34, v191
	v_add3_u32 v135, s34, v203, v198
	v_add_u32_e32 v102, v100, v193
	v_add_u32_e32 v100, v100, v192
	ds_read_b128 v[160:163], v100
	ds_read_b128 v[164:167], v102
	ds_read_b128 v[168:171], v100 offset:2048
	ds_read_b128 v[172:175], v102 offset:2048
	ds_read_b128 v[104:107], v100 offset:4096
	ds_read_b128 v[108:111], v102 offset:4096
	ds_read_b128 v[112:115], v100 offset:6144
	ds_read_b128 v[116:119], v102 offset:6144
	v_add_u32_e32 v103, v135, v199
	v_add_u32_e32 v133, v135, v200
	v_add_u32_e32 v134, v135, v201
	v_add_u32_e32 v135, v135, v202
	s_waitcnt lgkmcnt(4)
	v_mfma_f32_16x16x32_bf16 v[136:139], v[160:163], v[4:7], v[0:3]
	v_mfma_f32_16x16x32_bf16 v[140:143], v[168:171], v[4:7], v[0:3]
	v_mfma_f32_16x16x32_bf16 v[136:139], v[164:167], v[12:15], v[136:139]
	v_mfma_f32_16x16x32_bf16 v[140:143], v[172:175], v[12:15], v[140:143]
	ds_read_b64_tr_b16 v[216:217], v103 offset:8192
	ds_read_b64_tr_b16 v[218:219], v103 offset:10240
	ds_read_b64_tr_b16 v[220:221], v133 offset:8192
	ds_read_b64_tr_b16 v[222:223], v133 offset:10240
	ds_read_b64_tr_b16 v[224:225], v134 offset:8192
	ds_read_b64_tr_b16 v[226:227], v134 offset:10240
	ds_read_b64_tr_b16 v[228:229], v135 offset:8192
	ds_read_b64_tr_b16 v[230:231], v135 offset:10240
	v_mfma_f32_16x16x32_bf16 v[176:179], v[160:163], v[8:11], v[0:3]
	v_exp_f32_e32 v136, v136
	v_exp_f32_e32 v137, v137
	v_exp_f32_e32 v138, v138
	v_add_f32_e32 v144, v136, v137
	v_mfma_f32_16x16x32_bf16 v[232:235], v[168:171], v[8:11], v[0:3]
	v_exp_f32_e32 v139, v139
	v_add_f32_e32 v144, v144, v138
	v_exp_f32_e32 v140, v140
	v_add_f32_e32 v144, v144, v139
	v_mfma_f32_16x16x32_bf16 v[176:179], v[164:167], v[16:19], v[176:179]
	v_exp_f32_e32 v141, v141
	v_add_f32_e32 v144, v144, v140
	v_exp_f32_e32 v142, v142
	v_add_f32_e32 v144, v144, v141
	v_cvt_pk_bf16_f32 v136, v136, v137
	v_mfma_f32_16x16x32_bf16 v[232:235], v[172:175], v[16:19], v[232:235]
	v_exp_f32_e32 v143, v143
	v_add_f32_e32 v144, v144, v142
	v_cvt_pk_bf16_f32 v137, v138, v139
	v_cvt_pk_bf16_f32 v138, v140, v141
	v_cvt_pk_bf16_f32 v139, v142, v143
	v_add_f32_e32 v144, v144, v143
	v_add_f32_e32 v131, v131, v144
	s_waitcnt lgkmcnt(0)
; #define LAS __attribute__((address_space(3)))
; __device__ __forceinline__ s16x4 vtr(const LAS unsigned char* p) { return __builtin_bit_cast(s16x4, __builtin_amdgcn_ds_read_tr16_b64_v4i16((LAS v4i16_t*)p)); }
; __device__ __forceinline__ bf16x8 cat8(s16x4 a, s16x4 b) { return (bf16x8){a[0], a[1], a[2], a[3], b[0], b[1], b[2], b[3]}; }
; __device__ __forceinline__ bf16x8 pack8(const f32x4& a, const f32x4& b) { u32x4 w; w.x = pkbf(a[0], a[1]); w.y = pkbf(a[2], a[3]); w.z = pkbf(b[0], b[1]); w.w = pkbf(b[2], b[3]); return __builtin_bit_cast(bf16x8, w); }
;     ...
;     for (int gh = 0; gh < 4 / GPB; ++gh) {
;         f32x4 S[GPB][4];
; #pragma unroll
;         for (int kb = 0; kb < 4; ++kb) {
;             const bf16x8 kf0 = *(const LAS bf16x8*)(kb0 + (16 * kb) * 128 + kx0), kf1 = *(const LAS bf16x8*)(kb0 + (16 * kb) * 128 + kx1);
; #pragma unroll
;             for (int gi = 0; gi < GPB; ++gi) { S[gi][kb] = __builtin_amdgcn_mfma_f32_16x16x32_bf16(kf0, qf[GPB * gh + gi][0], cinit, 0, 0, 0);
;                 S[gi][kb] = __builtin_amdgcn_mfma_f32_16x16x32_bf16(kf1, qf[GPB * gh + gi][1], S[gi][kb], 0, 0, 0); } }
;         bf16x8 pf[GPB][2];
; #pragma unroll
;         for (int gi = 0; gi < GPB; ++gi) {
;             if (MASK) {
; #pragma unroll
;                 for (int kb = 0; kb < 4; ++kb)
; #pragma unroll
;                     for (int i = 0; i < 4; ++i) { const int rel = rel0 + 16 * kb + 4 * g + i; S[gi][kb][i] = ((unsigned)(rel + 128) > 256u) ? NEGBIG : S[gi][kb][i]; }
;             }
;             ls[GPB * gh + gi] += exp_step<4>(S[gi]);
;             pf[gi][0] = pack8(S[gi][0], S[gi][1]); pf[gi][1] = pack8(S[gi][2], S[gi][3]);
;         }
; #pragma unroll
;         for (int kc = 0; kc < 2; ++kc)
; #pragma unroll
;             for (int db = 0; db < 4; ++db) {
;                 const LAS unsigned char* va = vrow + ((db ^ swz) << 5) + (32 * kc) * 128;
;                 const bf16x8 vf = cat8(vtr(va), vtr(va + 16 * 128));
; #pragma unroll
;                 for (int gi = 0; gi < GPB; ++gi) O[GPB * gh + gi][db] = __builtin_amdgcn_mfma_f32_16x16x32_bf16(vf, pf[gi][kc], O[GPB * gh + gi][db], 0, 0, 0);
;             }
	v_mfma_f32_16x16x32_bf16 v[244:247], v[160:163], v[20:23], v[0:3]
	v_exp_f32_e32 v176, v176
	v_exp_f32_e32 v177, v177
	v_mfma_f32_16x16x32_bf16 v[248:251], v[168:171], v[20:23], v[0:3]
	v_exp_f32_e32 v178, v178
	v_add_f32_e32 v144, v176, v177
	v_mfma_f32_16x16x32_bf16 v[244:247], v[164:167], v[24:27], v[244:247]
	v_exp_f32_e32 v179, v179
	v_add_f32_e32 v144, v144, v178
	v_mfma_f32_16x16x32_bf16 v[248:251], v[172:175], v[24:27], v[248:251]
	v_exp_f32_e32 v232, v232
	v_add_f32_e32 v144, v144, v179
	v_mfma_f32_16x16x32_bf16 v[64:67], v[216:219], v[136:139], v[64:67]
	v_exp_f32_e32 v233, v233
	v_add_f32_e32 v144, v144, v232
	v_mfma_f32_16x16x32_bf16 v[60:63], v[220:223], v[136:139], v[60:63]
	v_exp_f32_e32 v234, v234
	v_add_f32_e32 v144, v144, v233
	v_cvt_pk_bf16_f32 v176, v176, v177
	v_mfma_f32_16x16x32_bf16 v[56:59], v[224:227], v[136:139], v[56:59]
	v_exp_f32_e32 v235, v235
	v_add_f32_e32 v144, v144, v234
	v_cvt_pk_bf16_f32 v177, v178, v179
	v_mfma_f32_16x16x32_bf16 v[52:55], v[228:231], v[136:139], v[52:55]
	v_cvt_pk_bf16_f32 v178, v232, v233
	v_cvt_pk_bf16_f32 v179, v234, v235
	v_add_f32_e32 v144, v144, v235
	v_add_f32_e32 v130, v130, v144
	v_mfma_f32_16x16x32_bf16 v[136:139], v[160:163], v[28:31], v[0:3]
	v_exp_f32_e32 v244, v244
	v_exp_f32_e32 v245, v245
	v_mfma_f32_16x16x32_bf16 v[140:143], v[168:171], v[28:31], v[0:3]
	v_exp_f32_e32 v246, v246
	v_add_f32_e32 v144, v244, v245
	v_mfma_f32_16x16x32_bf16 v[136:139], v[164:167], v[32:35], v[136:139]
	v_exp_f32_e32 v247, v247
	v_add_f32_e32 v144, v144, v246
	v_mfma_f32_16x16x32_bf16 v[140:143], v[172:175], v[32:35], v[140:143]
	v_exp_f32_e32 v248, v248
	v_add_f32_e32 v144, v144, v247
	v_mfma_f32_16x16x32_bf16 v[48:51], v[216:219], v[176:179], v[48:51]
	v_exp_f32_e32 v249, v249
	v_add_f32_e32 v144, v144, v248
	v_mfma_f32_16x16x32_bf16 v[44:47], v[220:223], v[176:179], v[44:47]
	v_exp_f32_e32 v250, v250
	v_add_f32_e32 v144, v144, v249
	v_cvt_pk_bf16_f32 v244, v244, v245
	v_mfma_f32_16x16x32_bf16 v[40:43], v[224:227], v[176:179], v[40:43]
	v_exp_f32_e32 v251, v251
	v_add_f32_e32 v144, v144, v250
	v_cvt_pk_bf16_f32 v245, v246, v247
	v_mfma_f32_16x16x32_bf16 v[36:39], v[228:231], v[176:179], v[36:39]
	v_cvt_pk_bf16_f32 v246, v248, v249
	v_cvt_pk_bf16_f32 v247, v250, v251
	v_add_f32_e32 v144, v144, v251
	v_add_f32_e32 v129, v129, v144
	ds_read_b64_tr_b16 v[160:161], v103 offset:12288
	ds_read_b64_tr_b16 v[162:163], v103 offset:14336
	ds_read_b64_tr_b16 v[164:165], v133 offset:12288
	ds_read_b64_tr_b16 v[166:167], v133 offset:14336
	ds_read_b64_tr_b16 v[168:169], v134 offset:12288
	ds_read_b64_tr_b16 v[170:171], v134 offset:14336
	ds_read_b64_tr_b16 v[172:173], v135 offset:12288
	ds_read_b64_tr_b16 v[174:175], v135 offset:14336
	v_mfma_f32_16x16x32_bf16 v[176:179], v[104:107], v[4:7], v[0:3]
	v_exp_f32_e32 v136, v136
	v_exp_f32_e32 v137, v137
	v_mfma_f32_16x16x32_bf16 v[232:235], v[112:115], v[4:7], v[0:3]
	v_exp_f32_e32 v138, v138
	v_add_f32_e32 v144, v136, v137
	v_mfma_f32_16x16x32_bf16 v[176:179], v[108:111], v[12:15], v[176:179]
	v_exp_f32_e32 v139, v139
	v_add_f32_e32 v144, v144, v138
	v_mfma_f32_16x16x32_bf16 v[232:235], v[116:119], v[12:15], v[232:235]
	v_exp_f32_e32 v140, v140
	v_add_f32_e32 v144, v144, v139
	v_mfma_f32_16x16x32_bf16 v[72:75], v[216:219], v[244:247], v[72:75]
	v_exp_f32_e32 v141, v141
	v_add_f32_e32 v144, v144, v140
	v_mfma_f32_16x16x32_bf16 v[84:87], v[220:223], v[244:247], v[84:87]
	v_exp_f32_e32 v142, v142
	v_add_f32_e32 v144, v144, v141
	v_cvt_pk_bf16_f32 v136, v136, v137
	v_mfma_f32_16x16x32_bf16 v[88:91], v[224:227], v[244:247], v[88:91]
	v_exp_f32_e32 v143, v143
	v_add_f32_e32 v144, v144, v142
	v_cvt_pk_bf16_f32 v137, v138, v139
	v_mfma_f32_16x16x32_bf16 v[96:99], v[228:231], v[244:247], v[96:99]
	v_cvt_pk_bf16_f32 v138, v140, v141
	v_cvt_pk_bf16_f32 v139, v142, v143
	v_add_f32_e32 v144, v144, v143
	v_add_f32_e32 v128, v128, v144
	v_mfma_f32_16x16x32_bf16 v[244:247], v[104:107], v[8:11], v[0:3]
	v_exp_f32_e32 v176, v176
	v_exp_f32_e32 v177, v177
	v_mfma_f32_16x16x32_bf16 v[248:251], v[112:115], v[8:11], v[0:3]
	v_exp_f32_e32 v178, v178
	v_add_f32_e32 v144, v176, v177
	v_mfma_f32_16x16x32_bf16 v[244:247], v[108:111], v[16:19], v[244:247]
	v_exp_f32_e32 v179, v179
	v_add_f32_e32 v144, v144, v178
	v_mfma_f32_16x16x32_bf16 v[248:251], v[116:119], v[16:19], v[248:251]
	v_exp_f32_e32 v232, v232
	v_add_f32_e32 v144, v144, v179
	v_mfma_f32_16x16x32_bf16 v[68:71], v[216:219], v[136:139], v[68:71]
	v_exp_f32_e32 v233, v233
	v_add_f32_e32 v144, v144, v232
	v_mfma_f32_16x16x32_bf16 v[76:79], v[220:223], v[136:139], v[76:79]
	v_exp_f32_e32 v234, v234
	v_add_f32_e32 v144, v144, v233
	v_cvt_pk_bf16_f32 v176, v176, v177
	v_mfma_f32_16x16x32_bf16 v[80:83], v[224:227], v[136:139], v[80:83]
	v_exp_f32_e32 v235, v235
	v_add_f32_e32 v144, v144, v234
	v_cvt_pk_bf16_f32 v177, v178, v179
	v_mfma_f32_16x16x32_bf16 v[92:95], v[228:231], v[136:139], v[92:95]
	v_cvt_pk_bf16_f32 v178, v232, v233
	v_cvt_pk_bf16_f32 v179, v234, v235
	v_add_f32_e32 v144, v144, v235
	v_add_f32_e32 v131, v131, v144
	s_waitcnt lgkmcnt(0)
; #define LAS __attribute__((address_space(3)))
; __device__ __forceinline__ s16x4 vtr(const LAS unsigned char* p) { return __builtin_bit_cast(s16x4, __builtin_amdgcn_ds_read_tr16_b64_v4i16((LAS v4i16_t*)p)); }
; __device__ __forceinline__ bf16x8 cat8(s16x4 a, s16x4 b) { return (bf16x8){a[0], a[1], a[2], a[3], b[0], b[1], b[2], b[3]}; }
;     ...
;         for (int kb = 0; kb < 4; ++kb) {
;             const bf16x8 kf0 = *(const LAS bf16x8*)(kb0 + (16 * kb) * 128 + kx0), kf1 = *(const LAS bf16x8*)(kb0 + (16 * kb) * 128 + kx1);
; #pragma unroll
;             for (int gi = 0; gi < GPB; ++gi) { S[gi][kb] = __builtin_amdgcn_mfma_f32_16x16x32_bf16(kf0, qf[GPB * gh + gi][0], cinit, 0, 0, 0);
;                 S[gi][kb] = __builtin_amdgcn_mfma_f32_16x16x32_bf16(kf1, qf[GPB * gh + gi][1], S[gi][kb], 0, 0, 0); } }
;         bf16x8 pf[GPB][2];
; #pragma unroll
;         for (int gi = 0; gi < GPB; ++gi) {
;             if (MASK) {
; #pragma unroll
;                 for (int kb = 0; kb < 4; ++kb)
; #pragma unroll
;                     for (int i = 0; i < 4; ++i) { const int rel = rel0 + 16 * kb + 4 * g + i; S[gi][kb][i] = ((unsigned)(rel + 128) > 256u) ? NEGBIG : S[gi][kb][i]; }
;             }
;             ls[GPB * gh + gi] += exp_step<4>(S[gi]);
;             pf[gi][0] = pack8(S[gi][0], S[gi][1]); pf[gi][1] = pack8(S[gi][2], S[gi][3]);
;         }
; #pragma unroll
;         for (int kc = 0; kc < 2; ++kc)
; #pragma unroll
;             for (int db = 0; db < 4; ++db) {
;                 const LAS unsigned char* va = vrow + ((db ^ swz) << 5) + (32 * kc) * 128;
;                 const bf16x8 vf = cat8(vtr(va), vtr(va + 16 * 128));
; #pragma unroll
;                 for (int gi = 0; gi < GPB; ++gi) O[GPB * gh + gi][db] = __builtin_amdgcn_mfma_f32_16x16x32_bf16(vf, pf[gi][kc], O[GPB * gh + gi][db], 0, 0, 0);
;             }
; __device__ __forceinline__ void swa_phase(LAS unsigned char* lds, const bf16_t* Q, const bf16_t* K, const bf16_t* V, bf16_t* Ob, const float* sink, float negb) {
;     ...
;         for (int t = 0; t < 4; ++t) {
;             dma_tile<1>(lds + ((t + 3) & 3) * SW_BUF, K, V, SW_ROW0(t + 3), 256, dl, w);
;             const LAS unsigned char* buf = lds + (t & 3) * SW_BUF;
;             full_tile<0, 2, 2>(O, ls, qf, negb, buf, buf + 8192, lane, 0);
;             ring_wait<2>();
	v_mfma_f32_16x16x32_bf16 v[136:139], v[104:107], v[20:23], v[0:3]
	v_exp_f32_e32 v244, v244
	v_exp_f32_e32 v245, v245
	v_mfma_f32_16x16x32_bf16 v[140:143], v[112:115], v[20:23], v[0:3]
	v_exp_f32_e32 v246, v246
	v_add_f32_e32 v144, v244, v245
	v_mfma_f32_16x16x32_bf16 v[136:139], v[108:111], v[24:27], v[136:139]
	v_exp_f32_e32 v247, v247
	v_add_f32_e32 v144, v144, v246
	v_mfma_f32_16x16x32_bf16 v[140:143], v[116:119], v[24:27], v[140:143]
	v_exp_f32_e32 v248, v248
	v_add_f32_e32 v144, v144, v247
	v_mfma_f32_16x16x32_bf16 v[64:67], v[160:163], v[176:179], v[64:67]
	v_exp_f32_e32 v249, v249
	v_add_f32_e32 v144, v144, v248
	v_mfma_f32_16x16x32_bf16 v[60:63], v[164:167], v[176:179], v[60:63]
	v_exp_f32_e32 v250, v250
	v_add_f32_e32 v144, v144, v249
	v_cvt_pk_bf16_f32 v244, v244, v245
	v_mfma_f32_16x16x32_bf16 v[56:59], v[168:171], v[176:179], v[56:59]
	v_exp_f32_e32 v251, v251
	v_add_f32_e32 v144, v144, v250
	v_cvt_pk_bf16_f32 v245, v246, v247
	v_mfma_f32_16x16x32_bf16 v[52:55], v[172:175], v[176:179], v[52:55]
	v_cvt_pk_bf16_f32 v246, v248, v249
	v_cvt_pk_bf16_f32 v247, v250, v251
	v_add_f32_e32 v144, v144, v251
	v_add_f32_e32 v130, v130, v144
	v_mfma_f32_16x16x32_bf16 v[176:179], v[104:107], v[28:31], v[0:3]
	v_exp_f32_e32 v136, v136
	v_exp_f32_e32 v137, v137
	v_mfma_f32_16x16x32_bf16 v[232:235], v[112:115], v[28:31], v[0:3]
	v_exp_f32_e32 v138, v138
	v_add_f32_e32 v144, v136, v137
	v_mfma_f32_16x16x32_bf16 v[176:179], v[108:111], v[32:35], v[176:179]
	v_exp_f32_e32 v139, v139
	v_add_f32_e32 v144, v144, v138
	v_mfma_f32_16x16x32_bf16 v[232:235], v[116:119], v[32:35], v[232:235]
	v_exp_f32_e32 v140, v140
	v_add_f32_e32 v144, v144, v139
	v_mfma_f32_16x16x32_bf16 v[48:51], v[160:163], v[244:247], v[48:51]
	v_exp_f32_e32 v141, v141
	v_add_f32_e32 v144, v144, v140
	v_mfma_f32_16x16x32_bf16 v[44:47], v[164:167], v[244:247], v[44:47]
	v_exp_f32_e32 v142, v142
	v_add_f32_e32 v144, v144, v141
	v_cvt_pk_bf16_f32 v136, v136, v137
	v_mfma_f32_16x16x32_bf16 v[40:43], v[168:171], v[244:247], v[40:43]
	v_exp_f32_e32 v143, v143
	v_add_f32_e32 v144, v144, v142
	v_cvt_pk_bf16_f32 v137, v138, v139
	v_mfma_f32_16x16x32_bf16 v[36:39], v[172:175], v[244:247], v[36:39]
	v_cvt_pk_bf16_f32 v138, v140, v141
	v_cvt_pk_bf16_f32 v139, v142, v143
	v_add_f32_e32 v144, v144, v143
	v_add_f32_e32 v129, v129, v144
	v_mfma_f32_16x16x32_bf16 v[72:75], v[160:163], v[136:139], v[72:75]
	v_exp_f32_e32 v176, v176
	v_exp_f32_e32 v177, v177
	v_exp_f32_e32 v178, v178
	v_add_f32_e32 v144, v176, v177
	v_mfma_f32_16x16x32_bf16 v[84:87], v[164:167], v[136:139], v[84:87]
	v_exp_f32_e32 v179, v179
	v_add_f32_e32 v144, v144, v178
	v_exp_f32_e32 v232, v232
	v_add_f32_e32 v144, v144, v179
	v_mfma_f32_16x16x32_bf16 v[88:91], v[168:171], v[136:139], v[88:91]
	v_exp_f32_e32 v233, v233
	v_add_f32_e32 v144, v144, v232
	v_exp_f32_e32 v234, v234
	v_add_f32_e32 v144, v144, v233
	v_cvt_pk_bf16_f32 v176, v176, v177
	v_mfma_f32_16x16x32_bf16 v[96:99], v[172:175], v[136:139], v[96:99]
	v_exp_f32_e32 v235, v235
	v_add_f32_e32 v144, v144, v234
	v_cvt_pk_bf16_f32 v177, v178, v179
	v_cvt_pk_bf16_f32 v178, v232, v233
	v_cvt_pk_bf16_f32 v179, v234, v235
	v_add_f32_e32 v144, v144, v235
	v_add_f32_e32 v128, v128, v144
	v_mfma_f32_16x16x32_bf16 v[68:71], v[160:163], v[176:179], v[68:71]
	v_mfma_f32_16x16x32_bf16 v[76:79], v[164:167], v[176:179], v[76:79]
	v_mfma_f32_16x16x32_bf16 v[80:83], v[168:171], v[176:179], v[80:83]
	v_mfma_f32_16x16x32_bf16 v[92:95], v[172:175], v[176:179], v[92:95]
	s_addk_i32 s1, 0x4000
	s_add_u32 s7, s7, 64
	s_addc_u32 s8, s8, 0
	s_add_i32 s6, s6, 1
	s_waitcnt vmcnt(4)
	s_barrier
	s_cmp_lt_u32 s6, s46
	s_cselect_b32 s11, s8, 0
	s_cselect_b32 s10, s7, s82
	s_lshl_b64 s[10:11], s[10:11], 9
	s_add_u32 s12, s67, s10
	s_addc_u32 s13, s4, s11
	s_add_u32 s10, s5, s10
	s_addc_u32 s11, s58, s11
	s_add_i32 s9, s40, s1
	s_mov_b32 s15, m0
	s_mov_b32 m0, s9
	s_nop 0
	global_load_lds_dwordx4 v212, s[12:13]
	s_mov_b32 m0, s15
	s_add_i32 s14, s9, 0x2000
	s_mov_b32 s9, m0
	s_mov_b32 m0, s14
	s_nop 0
	global_load_lds_dwordx4 v213, s[10:11]
	s_mov_b32 m0, s9
	s_add_i32 s34, s1, 0x4000
	v_add_u32_e32 v100, s34, v191
	v_add3_u32 v135, s34, v203, v198
	v_add_u32_e32 v102, v100, v193
	v_add_u32_e32 v100, v100, v192
	ds_read_b128 v[160:163], v100
	ds_read_b128 v[164:167], v102
	ds_read_b128 v[168:171], v100 offset:2048
	ds_read_b128 v[172:175], v102 offset:2048
	ds_read_b128 v[104:107], v100 offset:4096
	ds_read_b128 v[108:111], v102 offset:4096
	ds_read_b128 v[112:115], v100 offset:6144
	ds_read_b128 v[116:119], v102 offset:6144
	v_add_u32_e32 v103, v135, v199
	v_add_u32_e32 v133, v135, v200
	v_add_u32_e32 v134, v135, v201
	v_add_u32_e32 v135, v135, v202
	s_waitcnt lgkmcnt(4)
	v_mfma_f32_16x16x32_bf16 v[136:139], v[160:163], v[4:7], v[0:3]
	v_mfma_f32_16x16x32_bf16 v[140:143], v[168:171], v[4:7], v[0:3]
	v_mfma_f32_16x16x32_bf16 v[136:139], v[164:167], v[12:15], v[136:139]
	v_mfma_f32_16x16x32_bf16 v[140:143], v[172:175], v[12:15], v[140:143]
	ds_read_b64_tr_b16 v[216:217], v103 offset:8192
	ds_read_b64_tr_b16 v[218:219], v103 offset:10240
	ds_read_b64_tr_b16 v[220:221], v133 offset:8192
	ds_read_b64_tr_b16 v[222:223], v133 offset:10240
	ds_read_b64_tr_b16 v[224:225], v134 offset:8192
	ds_read_b64_tr_b16 v[226:227], v134 offset:10240
	ds_read_b64_tr_b16 v[228:229], v135 offset:8192
	ds_read_b64_tr_b16 v[230:231], v135 offset:10240
	v_mfma_f32_16x16x32_bf16 v[176:179], v[160:163], v[8:11], v[0:3]
	v_exp_f32_e32 v136, v136
	v_exp_f32_e32 v137, v137
	v_exp_f32_e32 v138, v138
	v_add_f32_e32 v144, v136, v137
	v_mfma_f32_16x16x32_bf16 v[232:235], v[168:171], v[8:11], v[0:3]
	v_exp_f32_e32 v139, v139
	v_add_f32_e32 v144, v144, v138
	v_exp_f32_e32 v140, v140
	v_add_f32_e32 v144, v144, v139
	v_mfma_f32_16x16x32_bf16 v[176:179], v[164:167], v[16:19], v[176:179]
	v_exp_f32_e32 v141, v141
	v_add_f32_e32 v144, v144, v140
	v_exp_f32_e32 v142, v142
	v_add_f32_e32 v144, v144, v141
	v_cvt_pk_bf16_f32 v136, v136, v137
	v_mfma_f32_16x16x32_bf16 v[232:235], v[172:175], v[16:19], v[232:235]
	v_exp_f32_e32 v143, v143
	v_add_f32_e32 v144, v144, v142
	v_cvt_pk_bf16_f32 v137, v138, v139
	v_cvt_pk_bf16_f32 v138, v140, v141
	v_cvt_pk_bf16_f32 v139, v142, v143
	v_add_f32_e32 v144, v144, v143
	v_add_f32_e32 v131, v131, v144
	s_waitcnt lgkmcnt(0)
; #define LAS __attribute__((address_space(3)))
; __device__ __forceinline__ s16x4 vtr(const LAS unsigned char* p) { return __builtin_bit_cast(s16x4, __builtin_amdgcn_ds_read_tr16_b64_v4i16((LAS v4i16_t*)p)); }
; __device__ __forceinline__ bf16x8 cat8(s16x4 a, s16x4 b) { return (bf16x8){a[0], a[1], a[2], a[3], b[0], b[1], b[2], b[3]}; }
; __device__ __forceinline__ bf16x8 pack8(const f32x4& a, const f32x4& b) { u32x4 w; w.x = pkbf(a[0], a[1]); w.y = pkbf(a[2], a[3]); w.z = pkbf(b[0], b[1]); w.w = pkbf(b[2], b[3]); return __builtin_bit_cast(bf16x8, w); }
;     ...
;     for (int gh = 0; gh < 4 / GPB; ++gh) {
;         f32x4 S[GPB][4];
; #pragma unroll
;         for (int kb = 0; kb < 4; ++kb) {
;             const bf16x8 kf0 = *(const LAS bf16x8*)(kb0 + (16 * kb) * 128 + kx0), kf1 = *(const LAS bf16x8*)(kb0 + (16 * kb) * 128 + kx1);
; #pragma unroll
;             for (int gi = 0; gi < GPB; ++gi) { S[gi][kb] = __builtin_amdgcn_mfma_f32_16x16x32_bf16(kf0, qf[GPB * gh + gi][0], cinit, 0, 0, 0);
;                 S[gi][kb] = __builtin_amdgcn_mfma_f32_16x16x32_bf16(kf1, qf[GPB * gh + gi][1], S[gi][kb], 0, 0, 0); } }
;         bf16x8 pf[GPB][2];
; #pragma unroll
;         for (int gi = 0; gi < GPB; ++gi) {
;             if (MASK) {
; #pragma unroll
;                 for (int kb = 0; kb < 4; ++kb)
; #pragma unroll
;                     for (int i = 0; i < 4; ++i) { const int rel = rel0 + 16 * kb + 4 * g + i; S[gi][kb][i] = ((unsigned)(rel + 128) > 256u) ? NEGBIG : S[gi][kb][i]; }
;             }
;             ls[GPB * gh + gi] += exp_step<4>(S[gi]);
;             pf[gi][0] = pack8(S[gi][0], S[gi][1]); pf[gi][1] = pack8(S[gi][2], S[gi][3]);
;         }
; #pragma unroll
;         for (int kc = 0; kc < 2; ++kc)
; #pragma unroll
;             for (int db = 0; db < 4; ++db) {
;                 const LAS unsigned char* va = vrow + ((db ^ swz) << 5) + (32 * kc) * 128;
;                 const bf16x8 vf = cat8(vtr(va), vtr(va + 16 * 128));
; #pragma unroll
;                 for (int gi = 0; gi < GPB; ++gi) O[GPB * gh + gi][db] = __builtin_amdgcn_mfma_f32_16x16x32_bf16(vf, pf[gi][kc], O[GPB * gh + gi][db], 0, 0, 0);
;             }
	v_mfma_f32_16x16x32_bf16 v[244:247], v[160:163], v[20:23], v[0:3]
	v_exp_f32_e32 v176, v176
	v_exp_f32_e32 v177, v177
	v_mfma_f32_16x16x32_bf16 v[248:251], v[168:171], v[20:23], v[0:3]
	v_exp_f32_e32 v178, v178
	v_add_f32_e32 v144, v176, v177
	v_mfma_f32_16x16x32_bf16 v[244:247], v[164:167], v[24:27], v[244:247]
	v_exp_f32_e32 v179, v179
	v_add_f32_e32 v144, v144, v178
	v_mfma_f32_16x16x32_bf16 v[248:251], v[172:175], v[24:27], v[248:251]
	v_exp_f32_e32 v232, v232
	v_add_f32_e32 v144, v144, v179
	v_mfma_f32_16x16x32_bf16 v[64:67], v[216:219], v[136:139], v[64:67]
	v_exp_f32_e32 v233, v233
	v_add_f32_e32 v144, v144, v232
	v_mfma_f32_16x16x32_bf16 v[60:63], v[220:223], v[136:139], v[60:63]
	v_exp_f32_e32 v234, v234
	v_add_f32_e32 v144, v144, v233
	v_cvt_pk_bf16_f32 v176, v176, v177
	v_mfma_f32_16x16x32_bf16 v[56:59], v[224:227], v[136:139], v[56:59]
	v_exp_f32_e32 v235, v235
	v_add_f32_e32 v144, v144, v234
	v_cvt_pk_bf16_f32 v177, v178, v179
	v_mfma_f32_16x16x32_bf16 v[52:55], v[228:231], v[136:139], v[52:55]
	v_cvt_pk_bf16_f32 v178, v232, v233
	v_cvt_pk_bf16_f32 v179, v234, v235
	v_add_f32_e32 v144, v144, v235
	v_add_f32_e32 v130, v130, v144
	v_mfma_f32_16x16x32_bf16 v[136:139], v[160:163], v[28:31], v[0:3]
	v_exp_f32_e32 v244, v244
	v_exp_f32_e32 v245, v245
	v_mfma_f32_16x16x32_bf16 v[140:143], v[168:171], v[28:31], v[0:3]
	v_exp_f32_e32 v246, v246
	v_add_f32_e32 v144, v244, v245
	v_mfma_f32_16x16x32_bf16 v[136:139], v[164:167], v[32:35], v[136:139]
	v_exp_f32_e32 v247, v247
	v_add_f32_e32 v144, v144, v246
	v_mfma_f32_16x16x32_bf16 v[140:143], v[172:175], v[32:35], v[140:143]
	v_exp_f32_e32 v248, v248
	v_add_f32_e32 v144, v144, v247
	v_mfma_f32_16x16x32_bf16 v[48:51], v[216:219], v[176:179], v[48:51]
	v_exp_f32_e32 v249, v249
	v_add_f32_e32 v144, v144, v248
	v_mfma_f32_16x16x32_bf16 v[44:47], v[220:223], v[176:179], v[44:47]
	v_exp_f32_e32 v250, v250
	v_add_f32_e32 v144, v144, v249
	v_cvt_pk_bf16_f32 v244, v244, v245
	v_mfma_f32_16x16x32_bf16 v[40:43], v[224:227], v[176:179], v[40:43]
	v_exp_f32_e32 v251, v251
	v_add_f32_e32 v144, v144, v250
	v_cvt_pk_bf16_f32 v245, v246, v247
	v_mfma_f32_16x16x32_bf16 v[36:39], v[228:231], v[176:179], v[36:39]
	v_cvt_pk_bf16_f32 v246, v248, v249
	v_cvt_pk_bf16_f32 v247, v250, v251
	v_add_f32_e32 v144, v144, v251
	v_add_f32_e32 v129, v129, v144
	ds_read_b64_tr_b16 v[160:161], v103 offset:12288
	ds_read_b64_tr_b16 v[162:163], v103 offset:14336
	ds_read_b64_tr_b16 v[164:165], v133 offset:12288
	ds_read_b64_tr_b16 v[166:167], v133 offset:14336
	ds_read_b64_tr_b16 v[168:169], v134 offset:12288
	ds_read_b64_tr_b16 v[170:171], v134 offset:14336
	ds_read_b64_tr_b16 v[172:173], v135 offset:12288
	ds_read_b64_tr_b16 v[174:175], v135 offset:14336
	v_mfma_f32_16x16x32_bf16 v[176:179], v[104:107], v[4:7], v[0:3]
	v_exp_f32_e32 v136, v136
	v_exp_f32_e32 v137, v137
	v_mfma_f32_16x16x32_bf16 v[232:235], v[112:115], v[4:7], v[0:3]
	v_exp_f32_e32 v138, v138
	v_add_f32_e32 v144, v136, v137
	v_mfma_f32_16x16x32_bf16 v[176:179], v[108:111], v[12:15], v[176:179]
	v_exp_f32_e32 v139, v139
	v_add_f32_e32 v144, v144, v138
	v_mfma_f32_16x16x32_bf16 v[232:235], v[116:119], v[12:15], v[232:235]
	v_exp_f32_e32 v140, v140
	v_add_f32_e32 v144, v144, v139
	v_mfma_f32_16x16x32_bf16 v[72:75], v[216:219], v[244:247], v[72:75]
	v_exp_f32_e32 v141, v141
	v_add_f32_e32 v144, v144, v140
	v_mfma_f32_16x16x32_bf16 v[84:87], v[220:223], v[244:247], v[84:87]
	v_exp_f32_e32 v142, v142
	v_add_f32_e32 v144, v144, v141
	v_cvt_pk_bf16_f32 v136, v136, v137
	v_mfma_f32_16x16x32_bf16 v[88:91], v[224:227], v[244:247], v[88:91]
	v_exp_f32_e32 v143, v143
	v_add_f32_e32 v144, v144, v142
	v_cvt_pk_bf16_f32 v137, v138, v139
	v_mfma_f32_16x16x32_bf16 v[96:99], v[228:231], v[244:247], v[96:99]
	v_cvt_pk_bf16_f32 v138, v140, v141
	v_cvt_pk_bf16_f32 v139, v142, v143
	v_add_f32_e32 v144, v144, v143
	v_add_f32_e32 v128, v128, v144
	v_mfma_f32_16x16x32_bf16 v[244:247], v[104:107], v[8:11], v[0:3]
	v_exp_f32_e32 v176, v176
	v_exp_f32_e32 v177, v177
	v_mfma_f32_16x16x32_bf16 v[248:251], v[112:115], v[8:11], v[0:3]
	v_exp_f32_e32 v178, v178
	v_add_f32_e32 v144, v176, v177
	v_mfma_f32_16x16x32_bf16 v[244:247], v[108:111], v[16:19], v[244:247]
	v_exp_f32_e32 v179, v179
	v_add_f32_e32 v144, v144, v178
	v_mfma_f32_16x16x32_bf16 v[248:251], v[116:119], v[16:19], v[248:251]
	v_exp_f32_e32 v232, v232
	v_add_f32_e32 v144, v144, v179
	v_mfma_f32_16x16x32_bf16 v[68:71], v[216:219], v[136:139], v[68:71]
	v_exp_f32_e32 v233, v233
	v_add_f32_e32 v144, v144, v232
	v_mfma_f32_16x16x32_bf16 v[76:79], v[220:223], v[136:139], v[76:79]
	v_exp_f32_e32 v234, v234
	v_add_f32_e32 v144, v144, v233
	v_cvt_pk_bf16_f32 v176, v176, v177
	v_mfma_f32_16x16x32_bf16 v[80:83], v[224:227], v[136:139], v[80:83]
	v_exp_f32_e32 v235, v235
	v_add_f32_e32 v144, v144, v234
	v_cvt_pk_bf16_f32 v177, v178, v179
	v_mfma_f32_16x16x32_bf16 v[92:95], v[228:231], v[136:139], v[92:95]
	v_cvt_pk_bf16_f32 v178, v232, v233
	v_cvt_pk_bf16_f32 v179, v234, v235
	v_add_f32_e32 v144, v144, v235
	v_add_f32_e32 v131, v131, v144
	s_waitcnt lgkmcnt(0)
; #define LAS __attribute__((address_space(3)))
; __device__ __forceinline__ s16x4 vtr(const LAS unsigned char* p) { return __builtin_bit_cast(s16x4, __builtin_amdgcn_ds_read_tr16_b64_v4i16((LAS v4i16_t*)p)); }
;     ...
;         for (int kb = 0; kb < 4; ++kb) {
;             const bf16x8 kf0 = *(const LAS bf16x8*)(kb0 + (16 * kb) * 128 + kx0), kf1 = *(const LAS bf16x8*)(kb0 + (16 * kb) * 128 + kx1);
; #pragma unroll
;             for (int gi = 0; gi < GPB; ++gi) { S[gi][kb] = __builtin_amdgcn_mfma_f32_16x16x32_bf16(kf0, qf[GPB * gh + gi][0], cinit, 0, 0, 0);
;                 S[gi][kb] = __builtin_amdgcn_mfma_f32_16x16x32_bf16(kf1, qf[GPB * gh + gi][1], S[gi][kb], 0, 0, 0); } }
;         bf16x8 pf[GPB][2];
; #pragma unroll
;         for (int gi = 0; gi < GPB; ++gi) {
;             if (MASK) {
; #pragma unroll
;                 for (int kb = 0; kb < 4; ++kb)
; #pragma unroll
;                     for (int i = 0; i < 4; ++i) { const int rel = rel0 + 16 * kb + 4 * g + i; S[gi][kb][i] = ((unsigned)(rel + 128) > 256u) ? NEGBIG : S[gi][kb][i]; }
;             }
;             ls[GPB * gh + gi] += exp_step<4>(S[gi]);
;             pf[gi][0] = pack8(S[gi][0], S[gi][1]); pf[gi][1] = pack8(S[gi][2], S[gi][3]);
;         }
; #pragma unroll
;         for (int kc = 0; kc < 2; ++kc)
; #pragma unroll
;             for (int db = 0; db < 4; ++db) {
;                 const LAS unsigned char* va = vrow + ((db ^ swz) << 5) + (32 * kc) * 128;
;                 const bf16x8 vf = cat8(vtr(va), vtr(va + 16 * 128));
; #pragma unroll
;                 for (int gi = 0; gi < GPB; ++gi) O[GPB * gh + gi][db] = __builtin_amdgcn_mfma_f32_16x16x32_bf16(vf, pf[gi][kc], O[GPB * gh + gi][db], 0, 0, 0);
;             }
; __device__ __forceinline__ void swa_phase(LAS unsigned char* lds, const bf16_t* Q, const bf16_t* K, const bf16_t* V, bf16_t* Ob, const float* sink, float negb) {
;     ...
;         for (int t = 4; t < NT; ++t) {
;             dma_tile<1>(lds + ((t + 3) & 3) * SW_BUF, K, V, SW_ROW0(t + 3), 256, dl, w);
;             const LAS unsigned char* buf = lds + (t & 3) * SW_BUF;
;             const int start = 128 * tb - 128 + 64 * (i_lo + t - 4);
;             if (start + 63 >= tq - 128 && start <= tq + 15 + 128)
;                 full_tile<1, 2, 2>(O, ls, qf, negb, buf, buf + 8192, lane, start - (tq + l15));
	v_mfma_f32_16x16x32_bf16 v[136:139], v[104:107], v[20:23], v[0:3]
	v_exp_f32_e32 v244, v244
	v_exp_f32_e32 v245, v245
	v_mfma_f32_16x16x32_bf16 v[140:143], v[112:115], v[20:23], v[0:3]
	v_exp_f32_e32 v246, v246
	v_add_f32_e32 v144, v244, v245
	v_mfma_f32_16x16x32_bf16 v[136:139], v[108:111], v[24:27], v[136:139]
	v_exp_f32_e32 v247, v247
	v_add_f32_e32 v144, v144, v246
	v_mfma_f32_16x16x32_bf16 v[140:143], v[116:119], v[24:27], v[140:143]
	v_exp_f32_e32 v248, v248
	v_add_f32_e32 v144, v144, v247
	v_mfma_f32_16x16x32_bf16 v[64:67], v[160:163], v[176:179], v[64:67]
	v_exp_f32_e32 v249, v249
	v_add_f32_e32 v144, v144, v248
	v_mfma_f32_16x16x32_bf16 v[60:63], v[164:167], v[176:179], v[60:63]
	v_exp_f32_e32 v250, v250
	v_add_f32_e32 v144, v144, v249
	v_cvt_pk_bf16_f32 v244, v244, v245
	v_mfma_f32_16x16x32_bf16 v[56:59], v[168:171], v[176:179], v[56:59]
	v_exp_f32_e32 v251, v251
	v_add_f32_e32 v144, v144, v250
	v_cvt_pk_bf16_f32 v245, v246, v247
	v_mfma_f32_16x16x32_bf16 v[52:55], v[172:175], v[176:179], v[52:55]
	v_cvt_pk_bf16_f32 v246, v248, v249
	v_cvt_pk_bf16_f32 v247, v250, v251
	v_add_f32_e32 v144, v144, v251
	v_add_f32_e32 v130, v130, v144
	v_mfma_f32_16x16x32_bf16 v[176:179], v[104:107], v[28:31], v[0:3]
	v_exp_f32_e32 v136, v136
	v_exp_f32_e32 v137, v137
	v_mfma_f32_16x16x32_bf16 v[232:235], v[112:115], v[28:31], v[0:3]
	v_exp_f32_e32 v138, v138
	v_add_f32_e32 v144, v136, v137
	v_mfma_f32_16x16x32_bf16 v[176:179], v[108:111], v[32:35], v[176:179]
	v_exp_f32_e32 v139, v139
	v_add_f32_e32 v144, v144, v138
	v_mfma_f32_16x16x32_bf16 v[232:235], v[116:119], v[32:35], v[232:235]
	v_exp_f32_e32 v140, v140
	v_add_f32_e32 v144, v144, v139
	v_mfma_f32_16x16x32_bf16 v[48:51], v[160:163], v[244:247], v[48:51]
	v_exp_f32_e32 v141, v141
	v_add_f32_e32 v144, v144, v140
	v_mfma_f32_16x16x32_bf16 v[44:47], v[164:167], v[244:247], v[44:47]
	v_exp_f32_e32 v142, v142
	v_add_f32_e32 v144, v144, v141
	v_cvt_pk_bf16_f32 v136, v136, v137
	v_mfma_f32_16x16x32_bf16 v[40:43], v[168:171], v[244:247], v[40:43]
	v_exp_f32_e32 v143, v143
	v_add_f32_e32 v144, v144, v142
	v_cvt_pk_bf16_f32 v137, v138, v139
	v_mfma_f32_16x16x32_bf16 v[36:39], v[172:175], v[244:247], v[36:39]
	v_cvt_pk_bf16_f32 v138, v140, v141
	v_cvt_pk_bf16_f32 v139, v142, v143
	v_add_f32_e32 v144, v144, v143
	v_add_f32_e32 v129, v129, v144
	v_mfma_f32_16x16x32_bf16 v[72:75], v[160:163], v[136:139], v[72:75]
	v_exp_f32_e32 v176, v176
	v_exp_f32_e32 v177, v177
	v_exp_f32_e32 v178, v178
	v_add_f32_e32 v144, v176, v177
	v_mfma_f32_16x16x32_bf16 v[84:87], v[164:167], v[136:139], v[84:87]
	v_exp_f32_e32 v179, v179
	v_add_f32_e32 v144, v144, v178
	v_exp_f32_e32 v232, v232
	v_add_f32_e32 v144, v144, v179
	v_mfma_f32_16x16x32_bf16 v[88:91], v[168:171], v[136:139], v[88:91]
	v_exp_f32_e32 v233, v233
	v_add_f32_e32 v144, v144, v232
	v_exp_f32_e32 v234, v234
	v_add_f32_e32 v144, v144, v233
	v_cvt_pk_bf16_f32 v176, v176, v177
	v_mfma_f32_16x16x32_bf16 v[96:99], v[172:175], v[136:139], v[96:99]
	v_exp_f32_e32 v235, v235
	v_add_f32_e32 v144, v144, v234
	v_cvt_pk_bf16_f32 v177, v178, v179
	v_cvt_pk_bf16_f32 v178, v232, v233
	v_cvt_pk_bf16_f32 v179, v234, v235
	v_add_f32_e32 v144, v144, v235
	v_add_f32_e32 v128, v128, v144
	v_mfma_f32_16x16x32_bf16 v[68:71], v[160:163], v[176:179], v[68:71]
	v_mfma_f32_16x16x32_bf16 v[76:79], v[164:167], v[176:179], v[76:79]
	v_mfma_f32_16x16x32_bf16 v[80:83], v[168:171], v[176:179], v[80:83]
	v_mfma_f32_16x16x32_bf16 v[92:95], v[172:175], v[176:179], v[92:95]
	s_addk_i32 s1, 0x4000
	s_add_u32 s7, s7, 64
	s_addc_u32 s8, s8, 0
	s_add_i32 s6, s6, 1
	s_waitcnt vmcnt(4)
	s_barrier
	s_add_i32 s48, s0, 0xffffff80
	s_add_i32 s49, s0, 0x8f
	s_add_i32 s50, s45, 0xffffffbf
	s_mov_b32 s51, 0
	s_mov_b32 s52, 0x10000
	v_mov_b32_e32 v132, v211
	s_branch .LBB0_355
